# q/kv up-projection epilogues: the eight per-row sum-of-squares loads hoisted to the epilogue start (one wait instead of eight serialized load waits)
# speedup vs baseline: 1.0552x; 1.0075x over previous
; __device__ __forceinline__ u32x4 pack8(f32x4 a, f32x4 b) { u32x4 w; w.x = cvt_pk_bf16(a[0], a[1]); w.y = cvt_pk_bf16(a[2], a[3]); w.z = cvt_pk_bf16(b[0], b[1]); w.w = cvt_pk_bf16(b[2], b[3]); return w; }
;     __device__ __forceinline__ void operator()(const f32x4 (&acc)[2][2][4][2], const Unit& u, int wr, int wc, int fr, int fq) const {
;     ...
;             for (int m = 0; m < 4; ++m) { const int row = row0 + ai * HALF + m * 16; bf16_t* rowp = O + (size_t)row * ld + c0;
;                 const float scr = rowss ? sc * (1.0f / sqrtf(rowss[row] * invn + 1e-6f)) : sc;
; #pragma unroll
;                 for (int bj = 0; bj < 2; ++bj) *(u32x4*)(rowp + bj * HALF) = pack8(acc[ai][bj][m][0] * scr, acc[ai][bj][m][1] * scr); }
.LBB0_480:
	v_lshl_add_u32 v144, s4, 8, v152
	v_ashrrev_i32_e32 v145, 31, v144
	v_lshl_add_u64 v[150:151], v[144:145], 2, s[10:11]
	global_load_dword v200, v[150:151], off
	global_load_dword v201, v[150:151], off offset:64
	global_load_dword v202, v[150:151], off offset:128
	global_load_dword v203, v[150:151], off offset:192
	global_load_dword v204, v[150:151], off offset:512
	global_load_dword v205, v[150:151], off offset:576
	global_load_dword v206, v[150:151], off offset:640
	global_load_dword v207, v[150:151], off offset:704
	v_mov_b64_e32 v[146:147], s[6:7]
	v_lshl_or_b32 v148, s5, 8, v154
	v_mad_i64_i32 v[160:161], s[4:5], v144, s49, v[146:147]
	v_or_b32_e32 v162, 16, v144
	v_ashrrev_i32_e32 v149, 31, v148
	v_lshlrev_b64 v[148:149], 1, v[148:149]
	v_lshl_add_u64 v[160:161], v[160:161], 0, v[148:149]
	s_waitcnt vmcnt(0)
	v_fmamk_f32 v145, v200, 0x3b000000, v158
	v_mul_f32_e32 v163, 0x4f800000, v145
	v_cmp_gt_f32_e32 vcc, s51, v145
	s_nop 1
	v_cndmask_b32_e32 v145, v145, v163, vcc
	v_sqrt_f32_e32 v164, v145
	v_ashrrev_i32_e32 v163, 31, v162
	v_add_u32_e32 v165, -1, v164
	v_add_u32_e32 v166, 1, v164
	v_fma_f32 v167, -v165, v164, v145
	v_fma_f32 v168, -v166, v164, v145
	v_cmp_ge_f32_e64 s[4:5], 0, v167
	s_nop 1
	v_cndmask_b32_e64 v164, v164, v165, s[4:5]
	v_cmp_lt_f32_e64 s[4:5], 0, v168
	s_nop 1
	v_cndmask_b32_e64 v164, v164, v166, s[4:5]
	v_mul_f32_e32 v165, 0x37800000, v164
	v_cndmask_b32_e32 v164, v164, v165, vcc
	v_cmp_class_f32_e32 vcc, v145, v159
	s_nop 1
	v_cndmask_b32_e32 v145, v164, v145, vcc
	v_div_scale_f32 v166, s[4:5], v145, v145, 1.0
	v_rcp_f32_e32 v167, v166
	v_lshl_add_u64 v[164:165], v[162:163], 2, s[10:11]
	v_div_scale_f32 v163, vcc, 1.0, v145, 1.0
	v_fma_f32 v168, -v166, v167, 1.0
	v_fmac_f32_e32 v167, v168, v167
	v_mul_f32_e32 v168, v163, v167
	v_fma_f32 v169, -v166, v168, v163
	v_fmac_f32_e32 v168, v169, v167
	v_fma_f32 v163, -v166, v168, v163
	v_div_fmas_f32 v163, v163, v167, v168
	v_div_fixup_f32 v145, v163, v145, 1.0
	v_mul_f32_e32 v166, 0x3dd53b94, v145
	v_pk_mul_f32 v[126:127], v[126:127], v[166:167] op_sel_hi:[1,0]
	v_pk_mul_f32 v[124:125], v[124:125], v[166:167] op_sel_hi:[1,0]
	v_pk_mul_f32 v[122:123], v[122:123], v[166:167] op_sel_hi:[1,0]
	v_pk_mul_f32 v[120:121], v[120:121], v[166:167] op_sel_hi:[1,0]
	v_pk_mul_f32 v[118:119], v[118:119], v[166:167] op_sel_hi:[1,0]
	v_pk_mul_f32 v[116:117], v[116:117], v[166:167] op_sel_hi:[1,0]
	v_pk_mul_f32 v[168:169], v[114:115], v[166:167] op_sel_hi:[1,0]
	v_pk_mul_f32 v[166:167], v[112:113], v[166:167] op_sel_hi:[1,0]
	v_cvt_pk_bf16_f32 v112, v124, v125
	v_cvt_pk_bf16_f32 v113, v126, v127
	v_cvt_pk_bf16_f32 v114, v120, v121
	v_cvt_pk_bf16_f32 v115, v122, v123
	v_cvt_pk_bf16_f32 v116, v116, v117
	v_cvt_pk_bf16_f32 v117, v118, v119
	s_nop 0
	v_cvt_pk_bf16_f32 v118, v166, v167
	v_cvt_pk_bf16_f32 v119, v168, v169
	global_store_dwordx4 v[160:161], v[112:115], off
	global_store_dwordx4 v[160:161], v[116:119], off offset:256
	s_nop 1
	v_or_b32_e32 v112, 32, v144
	s_nop 0
	v_fmamk_f32 v113, v201, 0x3b000000, v158
	v_mul_f32_e32 v114, 0x4f800000, v113
	v_cmp_gt_f32_e32 vcc, s51, v113
	s_nop 1
	v_cndmask_b32_e32 v116, v113, v114, vcc
	v_sqrt_f32_e32 v117, v116
	v_mad_i64_i32 v[114:115], s[4:5], v162, s49, v[146:147]
	v_ashrrev_i32_e32 v113, 31, v112
	v_add_u32_e32 v118, -1, v117
	v_add_u32_e32 v119, 1, v117
	v_fma_f32 v120, -v118, v117, v116
	v_fma_f32 v121, -v119, v117, v116
	v_cmp_ge_f32_e64 s[4:5], 0, v120
	v_lshl_add_u64 v[114:115], v[114:115], 0, v[148:149]
	s_nop 0
	v_cndmask_b32_e64 v117, v117, v118, s[4:5]
	v_cmp_lt_f32_e64 s[4:5], 0, v121
	s_nop 1
	v_cndmask_b32_e64 v117, v117, v119, s[4:5]
	v_mul_f32_e32 v118, 0x37800000, v117
	v_cndmask_b32_e32 v117, v117, v118, vcc
	v_cmp_class_f32_e32 vcc, v116, v159
	s_nop 1
	v_cndmask_b32_e32 v118, v117, v116, vcc
	v_div_scale_f32 v119, s[4:5], v118, v118, 1.0
	v_rcp_f32_e32 v120, v119
	v_lshl_add_u64 v[116:117], v[112:113], 2, s[10:11]
	v_div_scale_f32 v113, vcc, 1.0, v118, 1.0
	v_fma_f32 v121, -v119, v120, 1.0
	v_fmac_f32_e32 v120, v121, v120
	v_mul_f32_e32 v121, v113, v120
	v_fma_f32 v122, -v119, v121, v113
	v_fmac_f32_e32 v121, v122, v120
	v_fma_f32 v113, -v119, v121, v113
	v_div_fmas_f32 v113, v113, v120, v121
	v_div_fixup_f32 v113, v113, v118, 1.0
	v_mul_f32_e32 v118, 0x3dd53b94, v113
	v_pk_mul_f32 v[110:111], v[110:111], v[118:119] op_sel_hi:[1,0]
	v_pk_mul_f32 v[108:109], v[108:109], v[118:119] op_sel_hi:[1,0]
	v_pk_mul_f32 v[106:107], v[106:107], v[118:119] op_sel_hi:[1,0]
	v_pk_mul_f32 v[104:105], v[104:105], v[118:119] op_sel_hi:[1,0]
	v_pk_mul_f32 v[102:103], v[102:103], v[118:119] op_sel_hi:[1,0]
	v_pk_mul_f32 v[100:101], v[100:101], v[118:119] op_sel_hi:[1,0]
	v_pk_mul_f32 v[120:121], v[98:99], v[118:119] op_sel_hi:[1,0]
	v_pk_mul_f32 v[118:119], v[96:97], v[118:119] op_sel_hi:[1,0]
	v_cvt_pk_bf16_f32 v96, v108, v109
	v_cvt_pk_bf16_f32 v97, v110, v111
	v_cvt_pk_bf16_f32 v98, v104, v105
	v_cvt_pk_bf16_f32 v99, v106, v107
	v_cvt_pk_bf16_f32 v100, v100, v101
	v_cvt_pk_bf16_f32 v101, v102, v103
	s_nop 0
	v_cvt_pk_bf16_f32 v102, v118, v119
	v_cvt_pk_bf16_f32 v103, v120, v121
	global_store_dwordx4 v[114:115], v[96:99], off
	global_store_dwordx4 v[114:115], v[100:103], off offset:256
	s_nop 1
	v_or_b32_e32 v96, 48, v144
	s_nop 0
	v_fmamk_f32 v97, v202, 0x3b000000, v158
	v_mul_f32_e32 v98, 0x4f800000, v97
	v_cmp_gt_f32_e32 vcc, s51, v97
	s_nop 1
	v_cndmask_b32_e32 v100, v97, v98, vcc
	v_sqrt_f32_e32 v101, v100
	v_mad_i64_i32 v[98:99], s[4:5], v112, s49, v[146:147]
	v_ashrrev_i32_e32 v97, 31, v96
	v_add_u32_e32 v102, -1, v101
	v_add_u32_e32 v103, 1, v101
	v_fma_f32 v104, -v102, v101, v100
	v_fma_f32 v105, -v103, v101, v100
; __device__ __forceinline__ u32x4 pack8(f32x4 a, f32x4 b) { u32x4 w; w.x = cvt_pk_bf16(a[0], a[1]); w.y = cvt_pk_bf16(a[2], a[3]); w.z = cvt_pk_bf16(b[0], b[1]); w.w = cvt_pk_bf16(b[2], b[3]); return w; }
;     __device__ __forceinline__ void operator()(const f32x4 (&acc)[2][2][4][2], const Unit& u, int wr, int wc, int fr, int fq) const {
;     ...
;             for (int m = 0; m < 4; ++m) { const int row = row0 + ai * HALF + m * 16; bf16_t* rowp = O + (size_t)row * ld + c0;
;                 const float scr = rowss ? sc * (1.0f / sqrtf(rowss[row] * invn + 1e-6f)) : sc;
; #pragma unroll
;                 for (int bj = 0; bj < 2; ++bj) *(u32x4*)(rowp + bj * HALF) = pack8(acc[ai][bj][m][0] * scr, acc[ai][bj][m][1] * scr); }
	v_cmp_ge_f32_e64 s[4:5], 0, v104
	v_lshl_add_u64 v[98:99], v[98:99], 0, v[148:149]
	s_nop 0
	v_cndmask_b32_e64 v101, v101, v102, s[4:5]
	v_cmp_lt_f32_e64 s[4:5], 0, v105
	s_nop 1
	v_cndmask_b32_e64 v101, v101, v103, s[4:5]
	v_mul_f32_e32 v102, 0x37800000, v101
	v_cndmask_b32_e32 v101, v101, v102, vcc
	v_cmp_class_f32_e32 vcc, v100, v159
	s_nop 1
	v_cndmask_b32_e32 v102, v101, v100, vcc
	v_div_scale_f32 v103, s[4:5], v102, v102, 1.0
	v_rcp_f32_e32 v104, v103
	v_lshl_add_u64 v[100:101], v[96:97], 2, s[10:11]
	v_div_scale_f32 v97, vcc, 1.0, v102, 1.0
	v_fma_f32 v105, -v103, v104, 1.0
	v_fmac_f32_e32 v104, v105, v104
	v_mul_f32_e32 v105, v97, v104
	v_fma_f32 v106, -v103, v105, v97
	v_fmac_f32_e32 v105, v106, v104
	v_fma_f32 v97, -v103, v105, v97
	v_div_fmas_f32 v97, v97, v104, v105
	v_div_fixup_f32 v97, v97, v102, 1.0
	v_mul_f32_e32 v102, 0x3dd53b94, v97
	v_pk_mul_f32 v[94:95], v[94:95], v[102:103] op_sel_hi:[1,0]
	v_pk_mul_f32 v[92:93], v[92:93], v[102:103] op_sel_hi:[1,0]
	v_pk_mul_f32 v[90:91], v[90:91], v[102:103] op_sel_hi:[1,0]
	v_pk_mul_f32 v[88:89], v[88:89], v[102:103] op_sel_hi:[1,0]
	v_pk_mul_f32 v[86:87], v[86:87], v[102:103] op_sel_hi:[1,0]
	v_pk_mul_f32 v[84:85], v[84:85], v[102:103] op_sel_hi:[1,0]
	v_pk_mul_f32 v[104:105], v[82:83], v[102:103] op_sel_hi:[1,0]
	v_pk_mul_f32 v[102:103], v[80:81], v[102:103] op_sel_hi:[1,0]
	v_cvt_pk_bf16_f32 v80, v92, v93
	v_cvt_pk_bf16_f32 v81, v94, v95
	v_cvt_pk_bf16_f32 v82, v88, v89
	v_cvt_pk_bf16_f32 v83, v90, v91
	v_cvt_pk_bf16_f32 v84, v84, v85
	v_cvt_pk_bf16_f32 v85, v86, v87
	s_nop 0
	v_cvt_pk_bf16_f32 v86, v102, v103
	v_cvt_pk_bf16_f32 v87, v104, v105
	global_store_dwordx4 v[98:99], v[80:83], off
	global_store_dwordx4 v[98:99], v[84:87], off offset:256
	s_nop 1
	s_nop 0
	v_fmamk_f32 v80, v203, 0x3b000000, v158
	v_mul_f32_e32 v81, 0x4f800000, v80
	v_cmp_gt_f32_e32 vcc, s51, v80
	s_nop 1
	v_cndmask_b32_e32 v82, v80, v81, vcc
	v_sqrt_f32_e32 v83, v82
	v_mad_i64_i32 v[80:81], s[4:5], v96, s49, v[146:147]
	v_lshl_add_u64 v[80:81], v[80:81], 0, v[148:149]
	v_add_u32_e32 v84, -1, v83
	v_add_u32_e32 v85, 1, v83
	v_fma_f32 v86, -v84, v83, v82
	v_fma_f32 v87, -v85, v83, v82
	v_cmp_ge_f32_e64 s[4:5], 0, v86
	s_nop 1
	v_cndmask_b32_e64 v83, v83, v84, s[4:5]
	v_cmp_lt_f32_e64 s[4:5], 0, v87
	s_nop 1
	v_cndmask_b32_e64 v83, v83, v85, s[4:5]
	v_mul_f32_e32 v84, 0x37800000, v83
	v_cndmask_b32_e32 v83, v83, v84, vcc
	v_cmp_class_f32_e32 vcc, v82, v159
	s_nop 1
	v_cndmask_b32_e32 v82, v83, v82, vcc
	v_div_scale_f32 v83, s[4:5], v82, v82, 1.0
	v_rcp_f32_e32 v84, v83
	v_div_scale_f32 v85, vcc, 1.0, v82, 1.0
	v_fma_f32 v86, -v83, v84, 1.0
	v_fmac_f32_e32 v84, v86, v84
	v_mul_f32_e32 v86, v85, v84
	v_fma_f32 v87, -v83, v86, v85
	v_fmac_f32_e32 v86, v87, v84
	v_fma_f32 v83, -v83, v86, v85
	v_div_fmas_f32 v83, v83, v84, v86
	v_div_fixup_f32 v82, v83, v82, 1.0
	v_mul_f32_e32 v82, 0x3dd53b94, v82
	v_pk_mul_f32 v[78:79], v[78:79], v[82:83] op_sel_hi:[1,0]
	v_pk_mul_f32 v[76:77], v[76:77], v[82:83] op_sel_hi:[1,0]
	v_pk_mul_f32 v[74:75], v[74:75], v[82:83] op_sel_hi:[1,0]
	v_pk_mul_f32 v[72:73], v[72:73], v[82:83] op_sel_hi:[1,0]
	v_pk_mul_f32 v[70:71], v[70:71], v[82:83] op_sel_hi:[1,0]
	v_pk_mul_f32 v[68:69], v[68:69], v[82:83] op_sel_hi:[1,0]
	v_pk_mul_f32 v[84:85], v[66:67], v[82:83] op_sel_hi:[1,0]
	v_pk_mul_f32 v[82:83], v[64:65], v[82:83] op_sel_hi:[1,0]
	v_cvt_pk_bf16_f32 v64, v76, v77
	v_cvt_pk_bf16_f32 v65, v78, v79
	v_cvt_pk_bf16_f32 v66, v72, v73
	v_cvt_pk_bf16_f32 v67, v74, v75
	v_cvt_pk_bf16_f32 v68, v68, v69
	v_cvt_pk_bf16_f32 v69, v70, v71
	s_nop 0
	v_cvt_pk_bf16_f32 v70, v82, v83
	v_cvt_pk_bf16_f32 v71, v84, v85
	global_store_dwordx4 v[80:81], v[64:67], off
	global_store_dwordx4 v[80:81], v[68:71], off offset:256
	s_nop 1
	s_nop 0
	v_fmamk_f32 v64, v204, 0x3b000000, v158
	v_mul_f32_e32 v65, 0x4f800000, v64
	v_cmp_gt_f32_e32 vcc, s51, v64
	s_nop 1
	v_cndmask_b32_e32 v66, v64, v65, vcc
	v_sqrt_f32_e32 v67, v66
	v_add_u32_e32 v64, 0x80, v144
	v_mad_i64_i32 v[64:65], s[4:5], v64, s49, v[146:147]
	v_add_u32_e32 v68, -1, v67
	v_add_u32_e32 v69, 1, v67
	v_fma_f32 v70, -v68, v67, v66
	v_fma_f32 v71, -v69, v67, v66
	v_cmp_ge_f32_e64 s[4:5], 0, v70
	v_lshl_add_u64 v[64:65], v[64:65], 0, v[148:149]
	s_nop 0
	v_cndmask_b32_e64 v67, v67, v68, s[4:5]
	v_cmp_lt_f32_e64 s[4:5], 0, v71
	s_nop 1
	v_cndmask_b32_e64 v67, v67, v69, s[4:5]
	v_mul_f32_e32 v68, 0x37800000, v67
	v_cndmask_b32_e32 v67, v67, v68, vcc
	v_cmp_class_f32_e32 vcc, v66, v159
	s_nop 1
	v_cndmask_b32_e32 v66, v67, v66, vcc
	v_div_scale_f32 v67, s[4:5], v66, v66, 1.0
	v_rcp_f32_e32 v68, v67
	v_div_scale_f32 v69, vcc, 1.0, v66, 1.0
	v_fma_f32 v70, -v67, v68, 1.0
	v_fmac_f32_e32 v68, v70, v68
	v_mul_f32_e32 v70, v69, v68
	v_fma_f32 v71, -v67, v70, v69
	v_fmac_f32_e32 v70, v71, v68
	v_fma_f32 v67, -v67, v70, v69
	v_div_fmas_f32 v67, v67, v68, v70
	v_div_fixup_f32 v66, v67, v66, 1.0
	v_mul_f32_e32 v66, 0x3dd53b94, v66
	v_pk_mul_f32 v[62:63], v[62:63], v[66:67] op_sel_hi:[1,0]
	v_pk_mul_f32 v[60:61], v[60:61], v[66:67] op_sel_hi:[1,0]
	v_pk_mul_f32 v[58:59], v[58:59], v[66:67] op_sel_hi:[1,0]
	v_pk_mul_f32 v[56:57], v[56:57], v[66:67] op_sel_hi:[1,0]
	v_pk_mul_f32 v[54:55], v[54:55], v[66:67] op_sel_hi:[1,0]
	v_pk_mul_f32 v[52:53], v[52:53], v[66:67] op_sel_hi:[1,0]
	v_pk_mul_f32 v[68:69], v[50:51], v[66:67] op_sel_hi:[1,0]
	v_pk_mul_f32 v[66:67], v[48:49], v[66:67] op_sel_hi:[1,0]
	v_cvt_pk_bf16_f32 v48, v60, v61
	v_cvt_pk_bf16_f32 v49, v62, v63
	v_cvt_pk_bf16_f32 v50, v56, v57
	v_cvt_pk_bf16_f32 v51, v58, v59
	v_cvt_pk_bf16_f32 v52, v52, v53
	v_cvt_pk_bf16_f32 v53, v54, v55
	s_nop 0
	v_cvt_pk_bf16_f32 v54, v66, v67
	v_cvt_pk_bf16_f32 v55, v68, v69
; __device__ __forceinline__ u32x4 pack8(f32x4 a, f32x4 b) { u32x4 w; w.x = cvt_pk_bf16(a[0], a[1]); w.y = cvt_pk_bf16(a[2], a[3]); w.z = cvt_pk_bf16(b[0], b[1]); w.w = cvt_pk_bf16(b[2], b[3]); return w; }
;     __device__ __forceinline__ void operator()(const f32x4 (&acc)[2][2][4][2], const Unit& u, int wr, int wc, int fr, int fq) const {
;     ...
;             for (int m = 0; m < 4; ++m) { const int row = row0 + ai * HALF + m * 16; bf16_t* rowp = O + (size_t)row * ld + c0;
;                 const float scr = rowss ? sc * (1.0f / sqrtf(rowss[row] * invn + 1e-6f)) : sc;
; #pragma unroll
;                 for (int bj = 0; bj < 2; ++bj) *(u32x4*)(rowp + bj * HALF) = pack8(acc[ai][bj][m][0] * scr, acc[ai][bj][m][1] * scr); }
	global_store_dwordx4 v[64:65], v[48:51], off
	global_store_dwordx4 v[64:65], v[52:55], off offset:256
	s_nop 1
	s_nop 0
	v_fmamk_f32 v48, v205, 0x3b000000, v158
	v_mul_f32_e32 v49, 0x4f800000, v48
	v_cmp_gt_f32_e32 vcc, s51, v48
	s_nop 1
	v_cndmask_b32_e32 v50, v48, v49, vcc
	v_sqrt_f32_e32 v51, v50
	v_add_u32_e32 v48, 0x90, v144
	v_mad_i64_i32 v[48:49], s[4:5], v48, s49, v[146:147]
	v_add_u32_e32 v52, -1, v51
	v_add_u32_e32 v53, 1, v51
	v_fma_f32 v54, -v52, v51, v50
	v_fma_f32 v55, -v53, v51, v50
	v_cmp_ge_f32_e64 s[4:5], 0, v54
	v_lshl_add_u64 v[48:49], v[48:49], 0, v[148:149]
	s_nop 0
	v_cndmask_b32_e64 v51, v51, v52, s[4:5]
	v_cmp_lt_f32_e64 s[4:5], 0, v55
	s_nop 1
	v_cndmask_b32_e64 v51, v51, v53, s[4:5]
	v_mul_f32_e32 v52, 0x37800000, v51
	v_cndmask_b32_e32 v51, v51, v52, vcc
	v_cmp_class_f32_e32 vcc, v50, v159
	s_nop 1
	v_cndmask_b32_e32 v50, v51, v50, vcc
	v_div_scale_f32 v51, s[4:5], v50, v50, 1.0
	v_rcp_f32_e32 v52, v51
	v_div_scale_f32 v53, vcc, 1.0, v50, 1.0
	v_fma_f32 v54, -v51, v52, 1.0
	v_fmac_f32_e32 v52, v54, v52
	v_mul_f32_e32 v54, v53, v52
	v_fma_f32 v55, -v51, v54, v53
	v_fmac_f32_e32 v54, v55, v52
	v_fma_f32 v51, -v51, v54, v53
	v_div_fmas_f32 v51, v51, v52, v54
	v_div_fixup_f32 v50, v51, v50, 1.0
	v_mul_f32_e32 v50, 0x3dd53b94, v50
	v_pk_mul_f32 v[46:47], v[46:47], v[50:51] op_sel_hi:[1,0]
	v_pk_mul_f32 v[44:45], v[44:45], v[50:51] op_sel_hi:[1,0]
	v_pk_mul_f32 v[42:43], v[42:43], v[50:51] op_sel_hi:[1,0]
	v_pk_mul_f32 v[40:41], v[40:41], v[50:51] op_sel_hi:[1,0]
	v_pk_mul_f32 v[38:39], v[38:39], v[50:51] op_sel_hi:[1,0]
	v_pk_mul_f32 v[36:37], v[36:37], v[50:51] op_sel_hi:[1,0]
	v_pk_mul_f32 v[52:53], v[34:35], v[50:51] op_sel_hi:[1,0]
	v_pk_mul_f32 v[50:51], v[32:33], v[50:51] op_sel_hi:[1,0]
	v_cvt_pk_bf16_f32 v32, v44, v45
	v_cvt_pk_bf16_f32 v33, v46, v47
	v_cvt_pk_bf16_f32 v34, v40, v41
	v_cvt_pk_bf16_f32 v35, v42, v43
	v_cvt_pk_bf16_f32 v36, v36, v37
	v_cvt_pk_bf16_f32 v37, v38, v39
	s_nop 0
	v_cvt_pk_bf16_f32 v38, v50, v51
	v_cvt_pk_bf16_f32 v39, v52, v53
	global_store_dwordx4 v[48:49], v[32:35], off
	global_store_dwordx4 v[48:49], v[36:39], off offset:256
	s_nop 1
	s_nop 0
	v_fmamk_f32 v32, v206, 0x3b000000, v158
	v_mul_f32_e32 v33, 0x4f800000, v32
	v_cmp_gt_f32_e32 vcc, s51, v32
	s_nop 1
	v_cndmask_b32_e32 v34, v32, v33, vcc
	v_sqrt_f32_e32 v35, v34
	v_add_u32_e32 v32, 0xa0, v144
	v_mad_i64_i32 v[32:33], s[4:5], v32, s49, v[146:147]
	v_add_u32_e32 v36, -1, v35
	v_add_u32_e32 v37, 1, v35
	v_fma_f32 v38, -v36, v35, v34
	v_fma_f32 v39, -v37, v35, v34
	v_cmp_ge_f32_e64 s[4:5], 0, v38
	v_lshl_add_u64 v[32:33], v[32:33], 0, v[148:149]
	s_nop 0
	v_cndmask_b32_e64 v35, v35, v36, s[4:5]
	v_cmp_lt_f32_e64 s[4:5], 0, v39
	s_nop 1
	v_cndmask_b32_e64 v35, v35, v37, s[4:5]
	v_mul_f32_e32 v36, 0x37800000, v35
	v_cndmask_b32_e32 v35, v35, v36, vcc
	v_cmp_class_f32_e32 vcc, v34, v159
	s_nop 1
	v_cndmask_b32_e32 v34, v35, v34, vcc
	v_div_scale_f32 v35, s[4:5], v34, v34, 1.0
	v_rcp_f32_e32 v36, v35
	v_div_scale_f32 v37, vcc, 1.0, v34, 1.0
	v_fma_f32 v38, -v35, v36, 1.0
	v_fmac_f32_e32 v36, v38, v36
	v_mul_f32_e32 v38, v37, v36
	v_fma_f32 v39, -v35, v38, v37
	v_fmac_f32_e32 v38, v39, v36
	v_fma_f32 v35, -v35, v38, v37
	v_div_fmas_f32 v35, v35, v36, v38
	v_div_fixup_f32 v34, v35, v34, 1.0
	v_mul_f32_e32 v34, 0x3dd53b94, v34
	v_pk_mul_f32 v[30:31], v[30:31], v[34:35] op_sel_hi:[1,0]
	v_pk_mul_f32 v[28:29], v[28:29], v[34:35] op_sel_hi:[1,0]
	v_pk_mul_f32 v[26:27], v[26:27], v[34:35] op_sel_hi:[1,0]
	v_pk_mul_f32 v[24:25], v[24:25], v[34:35] op_sel_hi:[1,0]
	v_pk_mul_f32 v[22:23], v[22:23], v[34:35] op_sel_hi:[1,0]
	v_pk_mul_f32 v[20:21], v[20:21], v[34:35] op_sel_hi:[1,0]
	v_pk_mul_f32 v[36:37], v[18:19], v[34:35] op_sel_hi:[1,0]
	v_pk_mul_f32 v[34:35], v[16:17], v[34:35] op_sel_hi:[1,0]
	v_cvt_pk_bf16_f32 v16, v28, v29
	v_cvt_pk_bf16_f32 v17, v30, v31
	v_cvt_pk_bf16_f32 v18, v24, v25
	v_cvt_pk_bf16_f32 v19, v26, v27
	v_cvt_pk_bf16_f32 v20, v20, v21
	v_cvt_pk_bf16_f32 v21, v22, v23
	s_nop 0
	v_cvt_pk_bf16_f32 v22, v34, v35
	v_cvt_pk_bf16_f32 v23, v36, v37
	global_store_dwordx4 v[32:33], v[16:19], off
	global_store_dwordx4 v[32:33], v[20:23], off offset:256
	s_nop 1
	v_add_u32_e32 v17, 0xb0, v144
	s_nop 0
	v_fmamk_f32 v16, v207, 0x3b000000, v158
	v_mul_f32_e32 v18, 0x4f800000, v16
	v_cmp_gt_f32_e32 vcc, s51, v16
	s_nop 1
	v_cndmask_b32_e32 v18, v16, v18, vcc
	v_sqrt_f32_e32 v19, v18
	v_mad_i64_i32 v[16:17], s[4:5], v17, s49, v[146:147]
	v_lshl_add_u64 v[16:17], v[16:17], 0, v[148:149]
	v_add_u32_e32 v20, -1, v19
	v_add_u32_e32 v21, 1, v19
	v_fma_f32 v22, -v20, v19, v18
	v_fma_f32 v23, -v21, v19, v18
	v_cmp_ge_f32_e64 s[4:5], 0, v22
	s_nop 1
	v_cndmask_b32_e64 v19, v19, v20, s[4:5]
	v_cmp_lt_f32_e64 s[4:5], 0, v23
	s_nop 1
	v_cndmask_b32_e64 v19, v19, v21, s[4:5]
	v_mul_f32_e32 v20, 0x37800000, v19
	v_cndmask_b32_e32 v19, v19, v20, vcc
	v_cmp_class_f32_e32 vcc, v18, v159
	s_nop 1
	v_cndmask_b32_e32 v18, v19, v18, vcc
	v_div_scale_f32 v19, s[4:5], v18, v18, 1.0
	v_rcp_f32_e32 v20, v19
	v_div_scale_f32 v21, vcc, 1.0, v18, 1.0
	v_fma_f32 v22, -v19, v20, 1.0
	v_fmac_f32_e32 v20, v22, v20
	v_mul_f32_e32 v22, v21, v20
	v_fma_f32 v23, -v19, v22, v21
	v_fmac_f32_e32 v22, v23, v20
	v_fma_f32 v19, -v19, v22, v21
	v_div_fmas_f32 v19, v19, v20, v22
	v_div_fixup_f32 v18, v19, v18, 1.0
	v_mul_f32_e32 v18, 0x3dd53b94, v18
	s_andn2_b64 vcc, exec, s[2:3]
	v_pk_mul_f32 v[14:15], v[14:15], v[18:19] op_sel_hi:[1,0]
	v_pk_mul_f32 v[12:13], v[12:13], v[18:19] op_sel_hi:[1,0]
	v_pk_mul_f32 v[10:11], v[10:11], v[18:19] op_sel_hi:[1,0]
	v_pk_mul_f32 v[8:9], v[8:9], v[18:19] op_sel_hi:[1,0]
	v_pk_mul_f32 v[6:7], v[6:7], v[18:19] op_sel_hi:[1,0]
	v_pk_mul_f32 v[4:5], v[4:5], v[18:19] op_sel_hi:[1,0]
	v_pk_mul_f32 v[20:21], v[2:3], v[18:19] op_sel_hi:[1,0]
	v_pk_mul_f32 v[18:19], v[0:1], v[18:19] op_sel_hi:[1,0]
	v_cvt_pk_bf16_f32 v0, v12, v13
	v_cvt_pk_bf16_f32 v1, v14, v15
	v_cvt_pk_bf16_f32 v2, v8, v9
	v_cvt_pk_bf16_f32 v3, v10, v11
	s_mov_b64 s[2:3], -1
	v_cvt_pk_bf16_f32 v4, v4, v5
	v_cvt_pk_bf16_f32 v5, v6, v7
	v_cvt_pk_bf16_f32 v6, v18, v19
	v_cvt_pk_bf16_f32 v7, v20, v21
	global_store_dwordx4 v[16:17], v[0:3], off
	global_store_dwordx4 v[16:17], v[4:7], off offset:256
	s_cbranch_vccnz .LBB0_473
	s_andn2_b64 vcc, exec, s[8:9]
	s_cbranch_vccnz .LBB0_472
	s_barrier
	s_branch .LBB0_472

; __device__ __forceinline__ u32x4 pack8(f32x4 a, f32x4 b) { u32x4 w; w.x = cvt_pk_bf16(a[0], a[1]); w.y = cvt_pk_bf16(a[2], a[3]); w.z = cvt_pk_bf16(b[0], b[1]); w.w = cvt_pk_bf16(b[2], b[3]); return w; }
;     __device__ __forceinline__ void operator()(const f32x4 (&acc)[2][2][4][2], const Unit& u, int wr, int wc, int fr, int fq) const {
;     ...
;             for (int m = 0; m < 4; ++m) { const int row = row0 + ai * HALF + m * 16; const float scr = 1.0f / sqrtf(rowss[row] * (1.0f / 256.0f) + 1e-6f);
;                 *(u32x4*)(KN + (size_t)row * 2048 + h * 128 + cw) = pack8(acc[ai][0][m][0] * scr, acc[ai][0][m][1] * scr);
;                 *(u32x4*)(VT + (size_t)row * 2048 + h * 128 + cw) = pack8(acc[ai][1][m][0] * scr, acc[ai][1][m][1] * scr); }
.LBB0_498:
	v_lshl_add_u32 v146, s4, 8, v148
	v_ashrrev_i32_e32 v147, 31, v146
	v_lshl_add_u64 v[142:143], v[146:147], 2, s[12:13]
	global_load_dword v200, v[142:143], off
	global_load_dword v201, v[142:143], off offset:64
	global_load_dword v202, v[142:143], off offset:128
	global_load_dword v203, v[142:143], off offset:192
	global_load_dword v204, v[142:143], off offset:512
	global_load_dword v205, v[142:143], off offset:576
	global_load_dword v206, v[142:143], off offset:640
	global_load_dword v207, v[142:143], off offset:704
	v_lshlrev_b64 v[144:145], 12, v[146:147]
	s_lshl_b32 s4, s5, 7
	s_ashr_i32 s5, s4, 31
	s_lshl_b64 s[42:43], s[4:5], 1
	v_lshl_add_u64 v[158:159], s[8:9], 0, v[144:145]
	v_or_b32_e32 v156, 16, v146
	v_lshl_add_u64 v[160:161], s[10:11], 0, v[144:145]
	v_lshl_add_u64 v[158:159], v[158:159], 0, s[42:43]
	v_ashrrev_i32_e32 v157, 31, v156
	v_lshl_add_u64 v[160:161], v[160:161], 0, s[42:43]
	v_lshl_add_u64 v[158:159], v[158:159], 0, v[136:137]
	v_lshl_add_u64 v[162:163], v[156:157], 2, s[12:13]
	v_lshl_add_u64 v[160:161], v[160:161], 0, v[136:137]
	s_waitcnt vmcnt(0)
	v_fmamk_f32 v147, v200, 0x3b800000, v153
	v_mul_f32_e32 v155, 0x4f800000, v147
	v_cmp_gt_f32_e32 vcc, s64, v147
	s_nop 1
	v_cndmask_b32_e32 v147, v147, v155, vcc
	v_sqrt_f32_e32 v155, v147
	s_nop 0
	v_add_u32_e32 v164, -1, v155
	v_add_u32_e32 v165, 1, v155
	v_fma_f32 v166, -v164, v155, v147
	v_fma_f32 v167, -v165, v155, v147
	v_cmp_ge_f32_e64 s[4:5], 0, v166
	s_nop 1
	v_cndmask_b32_e64 v155, v155, v164, s[4:5]
	v_cmp_lt_f32_e64 s[4:5], 0, v167
	s_nop 1
	v_cndmask_b32_e64 v155, v155, v165, s[4:5]
	v_mul_f32_e32 v164, 0x37800000, v155
	v_cndmask_b32_e32 v155, v155, v164, vcc
	v_cmp_class_f32_e32 vcc, v147, v154
	s_nop 1
	v_cndmask_b32_e32 v147, v155, v147, vcc
	v_div_scale_f32 v155, s[4:5], v147, v147, 1.0
	v_rcp_f32_e32 v164, v155
	v_div_scale_f32 v165, vcc, 1.0, v147, 1.0
	v_fma_f32 v166, -v155, v164, 1.0
	v_fmac_f32_e32 v164, v166, v164
	v_mul_f32_e32 v166, v165, v164
	v_fma_f32 v167, -v155, v166, v165
	v_fmac_f32_e32 v166, v167, v164
	v_fma_f32 v155, -v155, v166, v165
	v_div_fmas_f32 v155, v155, v164, v166
	v_div_fixup_f32 v164, v155, v147, 1.0
	v_pk_mul_f32 v[114:115], v[114:115], v[164:165] op_sel_hi:[1,0]
	v_pk_mul_f32 v[112:113], v[112:113], v[164:165] op_sel_hi:[1,0]
	v_pk_mul_f32 v[118:119], v[118:119], v[164:165] op_sel_hi:[1,0]
	v_pk_mul_f32 v[116:117], v[116:117], v[164:165] op_sel_hi:[1,0]
	v_cvt_pk_bf16_f32 v112, v112, v113
	v_cvt_pk_bf16_f32 v113, v114, v115
	v_cvt_pk_bf16_f32 v115, v118, v119
	v_pk_mul_f32 v[122:123], v[122:123], v[164:165] op_sel_hi:[1,0]
	v_cvt_pk_bf16_f32 v114, v116, v117
	v_pk_mul_f32 v[120:121], v[120:121], v[164:165] op_sel_hi:[1,0]
	v_pk_mul_f32 v[126:127], v[126:127], v[164:165] op_sel_hi:[1,0]
	v_pk_mul_f32 v[124:125], v[124:125], v[164:165] op_sel_hi:[1,0]
	v_cvt_pk_bf16_f32 v116, v120, v121
	v_cvt_pk_bf16_f32 v117, v122, v123
	v_cvt_pk_bf16_f32 v119, v126, v127
	s_nop 0
	v_cvt_pk_bf16_f32 v118, v124, v125
	global_store_dwordx4 v[158:159], v[112:115], off
	global_store_dwordx4 v[160:161], v[116:119], off
	s_nop 1
	v_lshlrev_b64 v[114:115], 12, v[156:157]
	v_lshl_add_u64 v[118:119], s[8:9], 0, v[114:115]
	v_or_b32_e32 v112, 32, v146
	v_lshl_add_u64 v[114:115], s[10:11], 0, v[114:115]
	v_lshl_add_u64 v[118:119], v[118:119], 0, s[42:43]
	v_ashrrev_i32_e32 v113, 31, v112
	v_lshl_add_u64 v[114:115], v[114:115], 0, s[42:43]
	v_lshl_add_u64 v[118:119], v[118:119], 0, v[136:137]
	v_lshl_add_u64 v[116:117], v[112:113], 2, s[12:13]
	v_lshl_add_u64 v[114:115], v[114:115], 0, v[136:137]
	s_nop 0
	v_fmamk_f32 v120, v201, 0x3b800000, v153
	v_mul_f32_e32 v121, 0x4f800000, v120
	v_cmp_gt_f32_e32 vcc, s64, v120
	s_nop 1
	v_cndmask_b32_e32 v120, v120, v121, vcc
	v_sqrt_f32_e32 v121, v120
	s_nop 0
	v_add_u32_e32 v122, -1, v121
	v_add_u32_e32 v123, 1, v121
	v_fma_f32 v124, -v122, v121, v120
	v_fma_f32 v125, -v123, v121, v120
	v_cmp_ge_f32_e64 s[4:5], 0, v124
	s_nop 1
	v_cndmask_b32_e64 v121, v121, v122, s[4:5]
	v_cmp_lt_f32_e64 s[4:5], 0, v125
	s_nop 1
	v_cndmask_b32_e64 v121, v121, v123, s[4:5]
	v_mul_f32_e32 v122, 0x37800000, v121
	v_cndmask_b32_e32 v121, v121, v122, vcc
	v_cmp_class_f32_e32 vcc, v120, v154
	s_nop 1
	v_cndmask_b32_e32 v120, v121, v120, vcc
	v_div_scale_f32 v121, s[4:5], v120, v120, 1.0
	v_rcp_f32_e32 v122, v121
	v_div_scale_f32 v123, vcc, 1.0, v120, 1.0
	v_fma_f32 v124, -v121, v122, 1.0
	v_fmac_f32_e32 v122, v124, v122
	v_mul_f32_e32 v124, v123, v122
	v_fma_f32 v125, -v121, v124, v123
	v_fmac_f32_e32 v124, v125, v122
	v_fma_f32 v121, -v121, v124, v123
	v_div_fmas_f32 v121, v121, v122, v124
	v_div_fixup_f32 v120, v121, v120, 1.0
	v_pk_mul_f32 v[98:99], v[98:99], v[120:121] op_sel_hi:[1,0]
	v_pk_mul_f32 v[96:97], v[96:97], v[120:121] op_sel_hi:[1,0]
	v_pk_mul_f32 v[102:103], v[102:103], v[120:121] op_sel_hi:[1,0]
	v_pk_mul_f32 v[100:101], v[100:101], v[120:121] op_sel_hi:[1,0]
	v_cvt_pk_bf16_f32 v96, v96, v97
	v_cvt_pk_bf16_f32 v97, v98, v99
	v_cvt_pk_bf16_f32 v99, v102, v103
	v_pk_mul_f32 v[106:107], v[106:107], v[120:121] op_sel_hi:[1,0]
	v_cvt_pk_bf16_f32 v98, v100, v101
	v_pk_mul_f32 v[104:105], v[104:105], v[120:121] op_sel_hi:[1,0]
	v_pk_mul_f32 v[110:111], v[110:111], v[120:121] op_sel_hi:[1,0]
	v_pk_mul_f32 v[108:109], v[108:109], v[120:121] op_sel_hi:[1,0]
	v_cvt_pk_bf16_f32 v100, v104, v105
	v_cvt_pk_bf16_f32 v101, v106, v107
	v_cvt_pk_bf16_f32 v103, v110, v111
	s_nop 0
	v_cvt_pk_bf16_f32 v102, v108, v109
	global_store_dwordx4 v[118:119], v[96:99], off
	global_store_dwordx4 v[114:115], v[100:103], off
	s_nop 1
	v_lshlrev_b64 v[98:99], 12, v[112:113]
	v_lshl_add_u64 v[102:103], s[8:9], 0, v[98:99]
; __device__ __forceinline__ u32x4 pack8(f32x4 a, f32x4 b) { u32x4 w; w.x = cvt_pk_bf16(a[0], a[1]); w.y = cvt_pk_bf16(a[2], a[3]); w.z = cvt_pk_bf16(b[0], b[1]); w.w = cvt_pk_bf16(b[2], b[3]); return w; }
;     __device__ __forceinline__ void operator()(const f32x4 (&acc)[2][2][4][2], const Unit& u, int wr, int wc, int fr, int fq) const {
;     ...
;             for (int m = 0; m < 4; ++m) { const int row = row0 + ai * HALF + m * 16; const float scr = 1.0f / sqrtf(rowss[row] * (1.0f / 256.0f) + 1e-6f);
;                 *(u32x4*)(KN + (size_t)row * 2048 + h * 128 + cw) = pack8(acc[ai][0][m][0] * scr, acc[ai][0][m][1] * scr);
;                 *(u32x4*)(VT + (size_t)row * 2048 + h * 128 + cw) = pack8(acc[ai][1][m][0] * scr, acc[ai][1][m][1] * scr); }
	v_or_b32_e32 v96, 48, v146
	v_lshl_add_u64 v[98:99], s[10:11], 0, v[98:99]
	v_lshl_add_u64 v[102:103], v[102:103], 0, s[42:43]
	v_ashrrev_i32_e32 v97, 31, v96
	v_lshl_add_u64 v[98:99], v[98:99], 0, s[42:43]
	v_lshl_add_u64 v[102:103], v[102:103], 0, v[136:137]
	v_lshl_add_u64 v[100:101], v[96:97], 2, s[12:13]
	v_lshl_add_u64 v[98:99], v[98:99], 0, v[136:137]
	s_nop 0
	v_fmamk_f32 v104, v202, 0x3b800000, v153
	v_mul_f32_e32 v105, 0x4f800000, v104
	v_cmp_gt_f32_e32 vcc, s64, v104
	s_nop 1
	v_cndmask_b32_e32 v104, v104, v105, vcc
	v_sqrt_f32_e32 v105, v104
	s_nop 0
	v_add_u32_e32 v106, -1, v105
	v_add_u32_e32 v107, 1, v105
	v_fma_f32 v108, -v106, v105, v104
	v_fma_f32 v109, -v107, v105, v104
	v_cmp_ge_f32_e64 s[4:5], 0, v108
	s_nop 1
	v_cndmask_b32_e64 v105, v105, v106, s[4:5]
	v_cmp_lt_f32_e64 s[4:5], 0, v109
	s_nop 1
	v_cndmask_b32_e64 v105, v105, v107, s[4:5]
	v_mul_f32_e32 v106, 0x37800000, v105
	v_cndmask_b32_e32 v105, v105, v106, vcc
	v_cmp_class_f32_e32 vcc, v104, v154
	s_nop 1
	v_cndmask_b32_e32 v104, v105, v104, vcc
	v_div_scale_f32 v105, s[4:5], v104, v104, 1.0
	v_rcp_f32_e32 v106, v105
	v_div_scale_f32 v107, vcc, 1.0, v104, 1.0
	v_fma_f32 v108, -v105, v106, 1.0
	v_fmac_f32_e32 v106, v108, v106
	v_mul_f32_e32 v108, v107, v106
	v_fma_f32 v109, -v105, v108, v107
	v_fmac_f32_e32 v108, v109, v106
	v_fma_f32 v105, -v105, v108, v107
	v_div_fmas_f32 v105, v105, v106, v108
	v_div_fixup_f32 v104, v105, v104, 1.0
	v_pk_mul_f32 v[82:83], v[82:83], v[104:105] op_sel_hi:[1,0]
	v_pk_mul_f32 v[80:81], v[80:81], v[104:105] op_sel_hi:[1,0]
	v_pk_mul_f32 v[86:87], v[86:87], v[104:105] op_sel_hi:[1,0]
	v_pk_mul_f32 v[84:85], v[84:85], v[104:105] op_sel_hi:[1,0]
	v_cvt_pk_bf16_f32 v80, v80, v81
	v_cvt_pk_bf16_f32 v81, v82, v83
	v_cvt_pk_bf16_f32 v83, v86, v87
	v_pk_mul_f32 v[90:91], v[90:91], v[104:105] op_sel_hi:[1,0]
	v_cvt_pk_bf16_f32 v82, v84, v85
	v_pk_mul_f32 v[88:89], v[88:89], v[104:105] op_sel_hi:[1,0]
	v_pk_mul_f32 v[94:95], v[94:95], v[104:105] op_sel_hi:[1,0]
	v_pk_mul_f32 v[92:93], v[92:93], v[104:105] op_sel_hi:[1,0]
	v_cvt_pk_bf16_f32 v84, v88, v89
	v_cvt_pk_bf16_f32 v85, v90, v91
	v_cvt_pk_bf16_f32 v87, v94, v95
	s_nop 0
	v_cvt_pk_bf16_f32 v86, v92, v93
	global_store_dwordx4 v[102:103], v[80:83], off
	global_store_dwordx4 v[98:99], v[84:87], off
	s_nop 1
	v_lshlrev_b64 v[80:81], 12, v[96:97]
	v_lshl_add_u64 v[82:83], s[8:9], 0, v[80:81]
	v_lshl_add_u64 v[80:81], s[10:11], 0, v[80:81]
	v_lshl_add_u64 v[82:83], v[82:83], 0, s[42:43]
	v_lshl_add_u64 v[80:81], v[80:81], 0, s[42:43]
	v_lshl_add_u64 v[82:83], v[82:83], 0, v[136:137]
	v_lshl_add_u64 v[80:81], v[80:81], 0, v[136:137]
	s_nop 0
	v_fmamk_f32 v84, v203, 0x3b800000, v153
	v_mul_f32_e32 v85, 0x4f800000, v84
	v_cmp_gt_f32_e32 vcc, s64, v84
	s_nop 1
	v_cndmask_b32_e32 v84, v84, v85, vcc
	v_sqrt_f32_e32 v85, v84
	s_nop 0
	v_add_u32_e32 v86, -1, v85
	v_add_u32_e32 v87, 1, v85
	v_fma_f32 v88, -v86, v85, v84
	v_fma_f32 v89, -v87, v85, v84
	v_cmp_ge_f32_e64 s[4:5], 0, v88
	s_nop 1
	v_cndmask_b32_e64 v85, v85, v86, s[4:5]
	v_cmp_lt_f32_e64 s[4:5], 0, v89
	s_nop 1
	v_cndmask_b32_e64 v85, v85, v87, s[4:5]
	v_mul_f32_e32 v86, 0x37800000, v85
	v_cndmask_b32_e32 v85, v85, v86, vcc
	v_cmp_class_f32_e32 vcc, v84, v154
	s_nop 1
	v_cndmask_b32_e32 v84, v85, v84, vcc
	v_div_scale_f32 v85, s[4:5], v84, v84, 1.0
	v_rcp_f32_e32 v86, v85
	v_div_scale_f32 v87, vcc, 1.0, v84, 1.0
	v_fma_f32 v88, -v85, v86, 1.0
	v_fmac_f32_e32 v86, v88, v86
	v_mul_f32_e32 v88, v87, v86
	v_fma_f32 v89, -v85, v88, v87
	v_fmac_f32_e32 v88, v89, v86
	v_fma_f32 v85, -v85, v88, v87
	v_div_fmas_f32 v85, v85, v86, v88
	v_div_fixup_f32 v84, v85, v84, 1.0
	v_pk_mul_f32 v[66:67], v[66:67], v[84:85] op_sel_hi:[1,0]
	v_pk_mul_f32 v[64:65], v[64:65], v[84:85] op_sel_hi:[1,0]
	v_pk_mul_f32 v[70:71], v[70:71], v[84:85] op_sel_hi:[1,0]
	v_pk_mul_f32 v[68:69], v[68:69], v[84:85] op_sel_hi:[1,0]
	v_cvt_pk_bf16_f32 v64, v64, v65
	v_cvt_pk_bf16_f32 v65, v66, v67
	v_cvt_pk_bf16_f32 v67, v70, v71
	v_pk_mul_f32 v[74:75], v[74:75], v[84:85] op_sel_hi:[1,0]
	v_cvt_pk_bf16_f32 v66, v68, v69
	v_pk_mul_f32 v[72:73], v[72:73], v[84:85] op_sel_hi:[1,0]
	v_pk_mul_f32 v[78:79], v[78:79], v[84:85] op_sel_hi:[1,0]
	v_pk_mul_f32 v[76:77], v[76:77], v[84:85] op_sel_hi:[1,0]
	v_cvt_pk_bf16_f32 v68, v72, v73
	v_cvt_pk_bf16_f32 v69, v74, v75
	v_cvt_pk_bf16_f32 v71, v78, v79
	s_nop 0
	v_cvt_pk_bf16_f32 v70, v76, v77
	global_store_dwordx4 v[82:83], v[64:67], off
	global_store_dwordx4 v[80:81], v[68:71], off
	s_nop 1
	v_lshl_add_u64 v[64:65], v[144:145], 0, s[24:25]
	v_lshl_add_u64 v[66:67], s[8:9], 0, v[64:65]
	v_lshl_add_u64 v[64:65], s[10:11], 0, v[64:65]
	v_lshl_add_u64 v[66:67], v[66:67], 0, s[42:43]
	v_lshl_add_u64 v[64:65], v[64:65], 0, s[42:43]
	v_lshl_add_u64 v[66:67], v[66:67], 0, v[136:137]
	v_lshl_add_u64 v[64:65], v[64:65], 0, v[136:137]
	s_nop 0
	v_fmamk_f32 v68, v204, 0x3b800000, v153
	v_mul_f32_e32 v69, 0x4f800000, v68
	v_cmp_gt_f32_e32 vcc, s64, v68
	s_nop 1
	v_cndmask_b32_e32 v68, v68, v69, vcc
	v_sqrt_f32_e32 v69, v68
	s_nop 0
	v_add_u32_e32 v70, -1, v69
	v_add_u32_e32 v71, 1, v69
	v_fma_f32 v72, -v70, v69, v68
	v_fma_f32 v73, -v71, v69, v68
	v_cmp_ge_f32_e64 s[4:5], 0, v72
	s_nop 1
	v_cndmask_b32_e64 v69, v69, v70, s[4:5]
	v_cmp_lt_f32_e64 s[4:5], 0, v73
	s_nop 1
	v_cndmask_b32_e64 v69, v69, v71, s[4:5]
	v_mul_f32_e32 v70, 0x37800000, v69
	v_cndmask_b32_e32 v69, v69, v70, vcc
	v_cmp_class_f32_e32 vcc, v68, v154
	s_nop 1
	v_cndmask_b32_e32 v68, v69, v68, vcc
	v_div_scale_f32 v69, s[4:5], v68, v68, 1.0
	v_rcp_f32_e32 v70, v69
	v_div_scale_f32 v71, vcc, 1.0, v68, 1.0
	v_fma_f32 v72, -v69, v70, 1.0
	v_fmac_f32_e32 v70, v72, v70
	v_mul_f32_e32 v72, v71, v70
; __device__ __forceinline__ u32x4 pack8(f32x4 a, f32x4 b) { u32x4 w; w.x = cvt_pk_bf16(a[0], a[1]); w.y = cvt_pk_bf16(a[2], a[3]); w.z = cvt_pk_bf16(b[0], b[1]); w.w = cvt_pk_bf16(b[2], b[3]); return w; }
;     __device__ __forceinline__ void operator()(const f32x4 (&acc)[2][2][4][2], const Unit& u, int wr, int wc, int fr, int fq) const {
;     ...
;             for (int m = 0; m < 4; ++m) { const int row = row0 + ai * HALF + m * 16; const float scr = 1.0f / sqrtf(rowss[row] * (1.0f / 256.0f) + 1e-6f);
;                 *(u32x4*)(KN + (size_t)row * 2048 + h * 128 + cw) = pack8(acc[ai][0][m][0] * scr, acc[ai][0][m][1] * scr);
;                 *(u32x4*)(VT + (size_t)row * 2048 + h * 128 + cw) = pack8(acc[ai][1][m][0] * scr, acc[ai][1][m][1] * scr); }
	v_fma_f32 v73, -v69, v72, v71
	v_fmac_f32_e32 v72, v73, v70
	v_fma_f32 v69, -v69, v72, v71
	v_div_fmas_f32 v69, v69, v70, v72
	v_div_fixup_f32 v68, v69, v68, 1.0
	v_pk_mul_f32 v[50:51], v[50:51], v[68:69] op_sel_hi:[1,0]
	v_pk_mul_f32 v[48:49], v[48:49], v[68:69] op_sel_hi:[1,0]
	v_pk_mul_f32 v[54:55], v[54:55], v[68:69] op_sel_hi:[1,0]
	v_pk_mul_f32 v[52:53], v[52:53], v[68:69] op_sel_hi:[1,0]
	v_cvt_pk_bf16_f32 v48, v48, v49
	v_cvt_pk_bf16_f32 v49, v50, v51
	v_cvt_pk_bf16_f32 v51, v54, v55
	v_pk_mul_f32 v[58:59], v[58:59], v[68:69] op_sel_hi:[1,0]
	v_cvt_pk_bf16_f32 v50, v52, v53
	v_pk_mul_f32 v[56:57], v[56:57], v[68:69] op_sel_hi:[1,0]
	v_pk_mul_f32 v[62:63], v[62:63], v[68:69] op_sel_hi:[1,0]
	v_pk_mul_f32 v[60:61], v[60:61], v[68:69] op_sel_hi:[1,0]
	v_cvt_pk_bf16_f32 v52, v56, v57
	v_cvt_pk_bf16_f32 v53, v58, v59
	v_cvt_pk_bf16_f32 v55, v62, v63
	s_nop 0
	v_cvt_pk_bf16_f32 v54, v60, v61
	global_store_dwordx4 v[66:67], v[48:51], off
	global_store_dwordx4 v[64:65], v[52:55], off
	s_nop 1
	v_lshl_add_u64 v[48:49], v[144:145], 0, s[26:27]
	v_lshl_add_u64 v[50:51], s[8:9], 0, v[48:49]
	v_lshl_add_u64 v[48:49], s[10:11], 0, v[48:49]
	v_lshl_add_u64 v[50:51], v[50:51], 0, s[42:43]
	v_lshl_add_u64 v[48:49], v[48:49], 0, s[42:43]
	v_lshl_add_u64 v[50:51], v[50:51], 0, v[136:137]
	v_lshl_add_u64 v[48:49], v[48:49], 0, v[136:137]
	s_nop 0
	v_fmamk_f32 v52, v205, 0x3b800000, v153
	v_mul_f32_e32 v53, 0x4f800000, v52
	v_cmp_gt_f32_e32 vcc, s64, v52
	s_nop 1
	v_cndmask_b32_e32 v52, v52, v53, vcc
	v_sqrt_f32_e32 v53, v52
	s_nop 0
	v_add_u32_e32 v54, -1, v53
	v_add_u32_e32 v55, 1, v53
	v_fma_f32 v56, -v54, v53, v52
	v_fma_f32 v57, -v55, v53, v52
	v_cmp_ge_f32_e64 s[4:5], 0, v56
	s_nop 1
	v_cndmask_b32_e64 v53, v53, v54, s[4:5]
	v_cmp_lt_f32_e64 s[4:5], 0, v57
	s_nop 1
	v_cndmask_b32_e64 v53, v53, v55, s[4:5]
	v_mul_f32_e32 v54, 0x37800000, v53
	v_cndmask_b32_e32 v53, v53, v54, vcc
	v_cmp_class_f32_e32 vcc, v52, v154
	s_nop 1
	v_cndmask_b32_e32 v52, v53, v52, vcc
	v_div_scale_f32 v53, s[4:5], v52, v52, 1.0
	v_rcp_f32_e32 v54, v53
	v_div_scale_f32 v55, vcc, 1.0, v52, 1.0
	v_fma_f32 v56, -v53, v54, 1.0
	v_fmac_f32_e32 v54, v56, v54
	v_mul_f32_e32 v56, v55, v54
	v_fma_f32 v57, -v53, v56, v55
	v_fmac_f32_e32 v56, v57, v54
	v_fma_f32 v53, -v53, v56, v55
	v_div_fmas_f32 v53, v53, v54, v56
	v_div_fixup_f32 v52, v53, v52, 1.0
	v_pk_mul_f32 v[34:35], v[34:35], v[52:53] op_sel_hi:[1,0]
	v_pk_mul_f32 v[32:33], v[32:33], v[52:53] op_sel_hi:[1,0]
	v_pk_mul_f32 v[38:39], v[38:39], v[52:53] op_sel_hi:[1,0]
	v_pk_mul_f32 v[36:37], v[36:37], v[52:53] op_sel_hi:[1,0]
	v_cvt_pk_bf16_f32 v32, v32, v33
	v_cvt_pk_bf16_f32 v33, v34, v35
	v_cvt_pk_bf16_f32 v35, v38, v39
	v_pk_mul_f32 v[42:43], v[42:43], v[52:53] op_sel_hi:[1,0]
	v_cvt_pk_bf16_f32 v34, v36, v37
	v_pk_mul_f32 v[40:41], v[40:41], v[52:53] op_sel_hi:[1,0]
	v_pk_mul_f32 v[46:47], v[46:47], v[52:53] op_sel_hi:[1,0]
	v_pk_mul_f32 v[44:45], v[44:45], v[52:53] op_sel_hi:[1,0]
	v_cvt_pk_bf16_f32 v36, v40, v41
	v_cvt_pk_bf16_f32 v37, v42, v43
	v_cvt_pk_bf16_f32 v39, v46, v47
	s_nop 0
	v_cvt_pk_bf16_f32 v38, v44, v45
	global_store_dwordx4 v[50:51], v[32:35], off
	global_store_dwordx4 v[48:49], v[36:39], off
	s_nop 1
	v_lshl_add_u64 v[32:33], v[144:145], 0, s[28:29]
	v_lshl_add_u64 v[34:35], s[8:9], 0, v[32:33]
	v_lshl_add_u64 v[32:33], s[10:11], 0, v[32:33]
	v_lshl_add_u64 v[34:35], v[34:35], 0, s[42:43]
	v_lshl_add_u64 v[32:33], v[32:33], 0, s[42:43]
	v_lshl_add_u64 v[34:35], v[34:35], 0, v[136:137]
	v_lshl_add_u64 v[32:33], v[32:33], 0, v[136:137]
	s_nop 0
	v_fmamk_f32 v36, v206, 0x3b800000, v153
	v_mul_f32_e32 v37, 0x4f800000, v36
	v_cmp_gt_f32_e32 vcc, s64, v36
	s_nop 1
	v_cndmask_b32_e32 v36, v36, v37, vcc
	v_sqrt_f32_e32 v37, v36
	s_nop 0
	v_add_u32_e32 v38, -1, v37
	v_add_u32_e32 v39, 1, v37
	v_fma_f32 v40, -v38, v37, v36
	v_fma_f32 v41, -v39, v37, v36
; __device__ __forceinline__ u32x4 pack8(f32x4 a, f32x4 b) { u32x4 w; w.x = cvt_pk_bf16(a[0], a[1]); w.y = cvt_pk_bf16(a[2], a[3]); w.z = cvt_pk_bf16(b[0], b[1]); w.w = cvt_pk_bf16(b[2], b[3]); return w; }
;     __device__ __forceinline__ void operator()(const f32x4 (&acc)[2][2][4][2], const Unit& u, int wr, int wc, int fr, int fq) const {
;     ...
;             for (int m = 0; m < 4; ++m) { const int row = row0 + ai * HALF + m * 16; const float scr = 1.0f / sqrtf(rowss[row] * (1.0f / 256.0f) + 1e-6f);
;                 *(u32x4*)(KN + (size_t)row * 2048 + h * 128 + cw) = pack8(acc[ai][0][m][0] * scr, acc[ai][0][m][1] * scr);
;                 *(u32x4*)(VT + (size_t)row * 2048 + h * 128 + cw) = pack8(acc[ai][1][m][0] * scr, acc[ai][1][m][1] * scr); }
	v_cmp_ge_f32_e64 s[4:5], 0, v40
	s_nop 1
	v_cndmask_b32_e64 v37, v37, v38, s[4:5]
	v_cmp_lt_f32_e64 s[4:5], 0, v41
	s_nop 1
	v_cndmask_b32_e64 v37, v37, v39, s[4:5]
	v_mul_f32_e32 v38, 0x37800000, v37
	v_cndmask_b32_e32 v37, v37, v38, vcc
	v_cmp_class_f32_e32 vcc, v36, v154
	s_nop 1
	v_cndmask_b32_e32 v36, v37, v36, vcc
	v_div_scale_f32 v37, s[4:5], v36, v36, 1.0
	v_rcp_f32_e32 v38, v37
	v_div_scale_f32 v39, vcc, 1.0, v36, 1.0
	v_fma_f32 v40, -v37, v38, 1.0
	v_fmac_f32_e32 v38, v40, v38
	v_mul_f32_e32 v40, v39, v38
	v_fma_f32 v41, -v37, v40, v39
	v_fmac_f32_e32 v40, v41, v38
	v_fma_f32 v37, -v37, v40, v39
	v_div_fmas_f32 v37, v37, v38, v40
	v_div_fixup_f32 v36, v37, v36, 1.0
	v_pk_mul_f32 v[18:19], v[18:19], v[36:37] op_sel_hi:[1,0]
	v_pk_mul_f32 v[16:17], v[16:17], v[36:37] op_sel_hi:[1,0]
	v_pk_mul_f32 v[22:23], v[22:23], v[36:37] op_sel_hi:[1,0]
	v_pk_mul_f32 v[20:21], v[20:21], v[36:37] op_sel_hi:[1,0]
	v_cvt_pk_bf16_f32 v16, v16, v17
	v_cvt_pk_bf16_f32 v17, v18, v19
	v_cvt_pk_bf16_f32 v19, v22, v23
	v_pk_mul_f32 v[26:27], v[26:27], v[36:37] op_sel_hi:[1,0]
	v_cvt_pk_bf16_f32 v18, v20, v21
	v_pk_mul_f32 v[24:25], v[24:25], v[36:37] op_sel_hi:[1,0]
	v_pk_mul_f32 v[30:31], v[30:31], v[36:37] op_sel_hi:[1,0]
	v_pk_mul_f32 v[28:29], v[28:29], v[36:37] op_sel_hi:[1,0]
	v_cvt_pk_bf16_f32 v20, v24, v25
	v_cvt_pk_bf16_f32 v21, v26, v27
	v_cvt_pk_bf16_f32 v23, v30, v31
	s_nop 0
	v_cvt_pk_bf16_f32 v22, v28, v29
	global_store_dwordx4 v[34:35], v[16:19], off
	global_store_dwordx4 v[32:33], v[20:23], off
	s_nop 1
	v_lshl_add_u64 v[16:17], v[144:145], 0, s[30:31]
	v_lshl_add_u64 v[18:19], s[8:9], 0, v[16:17]
	v_lshl_add_u64 v[16:17], s[10:11], 0, v[16:17]
	v_lshl_add_u64 v[18:19], v[18:19], 0, s[42:43]
	v_lshl_add_u64 v[16:17], v[16:17], 0, s[42:43]
	v_lshl_add_u64 v[18:19], v[18:19], 0, v[136:137]
	v_lshl_add_u64 v[16:17], v[16:17], 0, v[136:137]
	s_nop 0
	v_fmamk_f32 v20, v207, 0x3b800000, v153
	v_mul_f32_e32 v21, 0x4f800000, v20
	v_cmp_gt_f32_e32 vcc, s64, v20
	s_nop 1
	v_cndmask_b32_e32 v20, v20, v21, vcc
	v_sqrt_f32_e32 v21, v20
	s_nop 0
	v_add_u32_e32 v22, -1, v21
	v_add_u32_e32 v23, 1, v21
	v_fma_f32 v24, -v22, v21, v20
	v_fma_f32 v25, -v23, v21, v20
	v_cmp_ge_f32_e64 s[4:5], 0, v24
	s_nop 1
	v_cndmask_b32_e64 v21, v21, v22, s[4:5]
	v_cmp_lt_f32_e64 s[4:5], 0, v25
	s_nop 1
	v_cndmask_b32_e64 v21, v21, v23, s[4:5]
	v_mul_f32_e32 v22, 0x37800000, v21
	v_cndmask_b32_e32 v21, v21, v22, vcc
	v_cmp_class_f32_e32 vcc, v20, v154
	s_nop 1
	v_cndmask_b32_e32 v20, v21, v20, vcc
	v_div_scale_f32 v21, s[4:5], v20, v20, 1.0
	v_rcp_f32_e32 v22, v21
	v_div_scale_f32 v23, vcc, 1.0, v20, 1.0
	v_fma_f32 v24, -v21, v22, 1.0
	v_fmac_f32_e32 v22, v24, v22
	v_mul_f32_e32 v24, v23, v22
	v_fma_f32 v25, -v21, v24, v23
	v_fmac_f32_e32 v24, v25, v22
	v_fma_f32 v21, -v21, v24, v23
	v_div_fmas_f32 v21, v21, v22, v24
	v_div_fixup_f32 v20, v21, v20, 1.0
	v_pk_mul_f32 v[2:3], v[2:3], v[20:21] op_sel_hi:[1,0]
	v_pk_mul_f32 v[0:1], v[0:1], v[20:21] op_sel_hi:[1,0]
	s_andn2_b64 vcc, exec, s[2:3]
	v_pk_mul_f32 v[6:7], v[6:7], v[20:21] op_sel_hi:[1,0]
	v_pk_mul_f32 v[4:5], v[4:5], v[20:21] op_sel_hi:[1,0]
	v_cvt_pk_bf16_f32 v0, v0, v1
	v_cvt_pk_bf16_f32 v1, v2, v3
	v_cvt_pk_bf16_f32 v3, v6, v7
	s_mov_b64 s[2:3], -1
	v_cvt_pk_bf16_f32 v2, v4, v5
	v_pk_mul_f32 v[10:11], v[10:11], v[20:21] op_sel_hi:[1,0]
	v_pk_mul_f32 v[8:9], v[8:9], v[20:21] op_sel_hi:[1,0]
	v_pk_mul_f32 v[14:15], v[14:15], v[20:21] op_sel_hi:[1,0]
	v_pk_mul_f32 v[12:13], v[12:13], v[20:21] op_sel_hi:[1,0]
	v_cvt_pk_bf16_f32 v4, v8, v9
	v_cvt_pk_bf16_f32 v5, v10, v11
	v_cvt_pk_bf16_f32 v7, v14, v15
	s_nop 0
	v_cvt_pk_bf16_f32 v6, v12, v13
	global_store_dwordx4 v[18:19], v[0:3], off
	global_store_dwordx4 v[16:17], v[4:7], off
	s_cbranch_vccnz .LBB0_489
	s_andn2_b64 vcc, exec, s[6:7]
	s_cbranch_vccnz .LBB0_488
	s_barrier
	s_branch .LBB0_488

; __device__ __forceinline__ u32x4 pack8(f32x4 a, f32x4 b) { u32x4 w; w.x = cvt_pk_bf16(a[0], a[1]); w.y = cvt_pk_bf16(a[2], a[3]); w.z = cvt_pk_bf16(b[0], b[1]); w.w = cvt_pk_bf16(b[2], b[3]); return w; }
;     __device__ __forceinline__ void operator()(const f32x4 (&acc)[2][2][4][2], const Unit& u, int wr, int wc, int fr, int fq) const {
;     ...
;             for (int m = 0; m < 4; ++m) { const int row = row0 + ai * HALF + m * 16; bf16_t* rowp = UP + (size_t)row * 5632 + u.pn * HALF + wc * 32 + 8 * fq;
; #pragma unroll
;                 for (int bj = 0; bj < 2; ++bj) { const u32x4 w = pack8(acc[ai][bj][m][0], acc[ai][bj][m][1]); __builtin_nontemporal_store(w, (u32x4*)(rowp + (size_t)bj * ((size_t)16384 * 5632)));
;                     if (m == 3 && fr >= 14) *(u32x4*)(HALO + ((size_t)(row >> 6) * 2 + (fr - 14)) * 11264 + c0 + bj * HALF) = w; } }
; __device__ __forceinline__ void phase10(const Args& a, int G, int wv, bool dummy = false) {
;     ...
;         const f32x4 wg0 = *(const f32x4*)(cw + ch), wg1 = *(const f32x4*)(cw + 11264 + ch), wg2 = *(const f32x4*)(cw + 22528 + ch), bg = *(const f32x4*)(cb + ch);
;         const f32x4 wv0 = *(const f32x4*)(cw + 5632 + ch), wv1 = *(const f32x4*)(cw + 11264 + 5632 + ch), wv2 = *(const f32x4*)(cw + 22528 + 5632 + ch), bv = *(const f32x4*)(cb + 5632 + ch);
;         f32x4 gm2 = {0.f, 0.f, 0.f, 0.f}, gm1 = gm2, vm2 = gm2, vm1 = gm2;
.LBB0_968:
	s_mov_b32 s98, s28
	s_mov_b32 s99, s29
	s_load_dwordx4 s[28:31], s[0:1], 0xa8
	v_lshlrev_b32_e32 v148, 2, v152
	v_add_u32_e32 v149, s52, v150
	v_mul_u32_u24_e32 v149, 0x2c00, v149
	v_lshl_add_u32 v149, v152, 1, v149
	v_mul_u32_u24_e32 v221, 0x5800, v150
	v_lshl_add_u32 v221, v152, 1, v221
	v_add_u32_e32 v220, 0xfffb3000, v221
	v_cmp_gt_u32_e64 s[64:65], 2, v150
	v_mov_b32_e32 v236, 0xbfb8aa3b
	v_mov_b32_e32 v238, 1.0
	v_mov_b32_e32 v239, 1.0
	s_lshl_b32 s21, s99, 9
	s_waitcnt lgkmcnt(0)
	s_add_u32 s100, s28, s21
	s_addc_u32 s101, s29, 0
	global_load_dwordx4 v[156:159], v148, s[100:101]
	global_load_dwordx4 v[160:163], v148, s[100:101] offset:16
	s_add_u32 s36, s100, 0xb000
	s_addc_u32 s37, s101, 0
	global_load_dwordx4 v[164:167], v148, s[36:37]
	global_load_dwordx4 v[168:171], v148, s[36:37] offset:16
	s_add_u32 s36, s100, 0x16000
	s_addc_u32 s37, s101, 0
	global_load_dwordx4 v[172:175], v148, s[36:37]
	global_load_dwordx4 v[176:179], v148, s[36:37] offset:16
	s_add_u32 s36, s100, 0x5800
	s_addc_u32 s37, s101, 0
	global_load_dwordx4 v[188:191], v148, s[36:37]
	global_load_dwordx4 v[192:195], v148, s[36:37] offset:16
	s_add_u32 s36, s100, 0x10800
	s_addc_u32 s37, s101, 0
	global_load_dwordx4 v[196:199], v148, s[36:37]
	global_load_dwordx4 v[200:203], v148, s[36:37] offset:16
	s_add_u32 s36, s100, 0x1b800
	s_addc_u32 s37, s101, 0
	global_load_dwordx4 v[204:207], v148, s[36:37]
	global_load_dwordx4 v[208:211], v148, s[36:37] offset:16
	s_add_u32 s100, s30, s21
	s_addc_u32 s101, s31, 0
	global_load_dwordx4 v[180:183], v148, s[100:101]
	global_load_dwordx4 v[184:187], v148, s[100:101] offset:16
	s_add_u32 s36, s100, 0x5800
	s_addc_u32 s37, s101, 0
	global_load_dwordx4 v[212:215], v148, s[36:37]
	global_load_dwordx4 v[216:219], v148, s[36:37] offset:16
	s_lshl_b32 s63, s98, 2
	s_lshr_b32 s66, s52, 6
	s_add_i32 s63, s63, s66
	s_mul_i32 s63, s63, 0xb000
	s_add_i32 s63, s63, s21
	s_add_u32 s34, s14, s63
	s_addc_u32 s35, s15, 0
	s_add_u32 s36, s12, 0xb000000
	s_addc_u32 s37, s13, 0
	s_add_u32 s36, s36, s63
	s_addc_u32 s37, s37, 0
	v_cvt_pk_bf16_f32 v222, v80, v81
	v_cvt_pk_bf16_f32 v223, v82, v83
	v_cvt_pk_bf16_f32 v224, v72, v73
	v_cvt_pk_bf16_f32 v225, v74, v75
	s_mov_b64 exec, s[2:3]
	global_store_dwordx4 v220, v[222:225], s[34:35]
	s_mov_b64 exec, -1
	v_cvt_pk_bf16_f32 v226, v68, v69
	v_cvt_pk_bf16_f32 v227, v70, v71
	v_cvt_pk_bf16_f32 v228, v64, v65
	v_cvt_pk_bf16_f32 v229, v66, v67
	s_mov_b64 exec, s[2:3]
	global_store_dwordx4 v220, v[226:229], s[34:35] offset:256
	s_mov_b64 exec, -1
	v_cvt_pk_bf16_f32 v230, v124, v125
	v_cvt_pk_bf16_f32 v231, v126, v127
	v_cvt_pk_bf16_f32 v232, v120, v121
	v_cvt_pk_bf16_f32 v233, v122, v123
	s_mov_b64 exec, s[64:65]
	global_store_dwordx4 v221, v[230:233], s[36:37]
	s_mov_b64 exec, -1
	v_cvt_pk_bf16_f32 v240, v116, v117
	v_cvt_pk_bf16_f32 v241, v118, v119
	v_cvt_pk_bf16_f32 v242, v108, v109
	v_cvt_pk_bf16_f32 v243, v110, v111
	s_mov_b64 exec, s[64:65]
	global_store_dwordx4 v221, v[240:243], s[36:37] offset:256
	s_mov_b64 exec, -1
	s_add_u32 s34, s34, 0x16000
	s_addc_u32 s35, s35, 0
	s_add_u32 s36, s36, 0x16000
	s_addc_u32 s37, s37, 0
	v_cvt_pk_bf16_f32 v222, v16, v17
	v_cvt_pk_bf16_f32 v223, v18, v19
	v_cvt_pk_bf16_f32 v224, v8, v9
	v_cvt_pk_bf16_f32 v225, v10, v11
	s_mov_b64 exec, s[2:3]
	global_store_dwordx4 v220, v[222:225], s[34:35]
	s_mov_b64 exec, -1
	v_cvt_pk_bf16_f32 v226, v4, v5
	v_cvt_pk_bf16_f32 v227, v6, v7
	v_cvt_pk_bf16_f32 v228, v0, v1
	v_cvt_pk_bf16_f32 v229, v2, v3
	s_mov_b64 exec, s[2:3]
	global_store_dwordx4 v220, v[226:229], s[34:35] offset:256
	s_mov_b64 exec, -1
	v_cvt_pk_bf16_f32 v230, v60, v61
	v_cvt_pk_bf16_f32 v231, v62, v63
	v_cvt_pk_bf16_f32 v232, v56, v57
	v_cvt_pk_bf16_f32 v233, v58, v59
	s_mov_b64 exec, s[64:65]
	global_store_dwordx4 v221, v[230:233], s[36:37]
	s_mov_b64 exec, -1
	v_cvt_pk_bf16_f32 v240, v52, v53
	v_cvt_pk_bf16_f32 v241, v54, v55
	v_cvt_pk_bf16_f32 v242, v44, v45
	v_cvt_pk_bf16_f32 v243, v46, v47
	s_mov_b64 exec, s[64:65]
	global_store_dwordx4 v221, v[240:243], s[36:37] offset:256
	s_mov_b64 exec, -1
	s_waitcnt vmcnt(0)
	s_nop 4
	s_mul_i32 s63, s98, 0x2c0000
	s_lshl_b32 s66, s99, 8
	s_add_u32 s63, s63, s66
	s_add_u32 s100, s12, s63
	s_addc_u32 s101, s13, 0
	v_pk_fma_f32 v[232:233], v[80:81], v[172:173], v[180:181]
	v_pk_fma_f32 v[234:235], v[68:69], v[204:205], v[212:213]
	s_nop 1
	v_fmac_f32_dpp v232, v80, v164 row_shr:1 row_mask:0xf bank_mask:0xf
	v_fmac_f32_dpp v233, v81, v165 row_shr:1 row_mask:0xf bank_mask:0xf
	v_fmac_f32_dpp v234, v68, v196 row_shr:1 row_mask:0xf bank_mask:0xf
	v_fmac_f32_dpp v235, v69, v197 row_shr:1 row_mask:0xf bank_mask:0xf
	v_fmac_f32_dpp v232, v80, v156 row_shr:2 row_mask:0xf bank_mask:0xf
	v_fmac_f32_dpp v233, v81, v157 row_shr:2 row_mask:0xf bank_mask:0xf
	v_fmac_f32_dpp v234, v68, v188 row_shr:2 row_mask:0xf bank_mask:0xf
	v_fmac_f32_dpp v235, v69, v189 row_shr:2 row_mask:0xf bank_mask:0xf
	v_fmac_f32_dpp v232, v96, v164 row_shl:15 row_mask:0xf bank_mask:0xf
	v_fmac_f32_dpp v233, v97, v165 row_shl:15 row_mask:0xf bank_mask:0xf
	v_fmac_f32_dpp v234, v84, v196 row_shl:15 row_mask:0xf bank_mask:0xf
	v_fmac_f32_dpp v235, v85, v197 row_shl:15 row_mask:0xf bank_mask:0xf
	v_fmac_f32_dpp v232, v96, v156 row_shl:14 row_mask:0xf bank_mask:0xf
	v_fmac_f32_dpp v233, v97, v157 row_shl:14 row_mask:0xf bank_mask:0xf
	v_fmac_f32_dpp v234, v84, v188 row_shl:14 row_mask:0xf bank_mask:0xf
	v_fmac_f32_dpp v235, v85, v189 row_shl:14 row_mask:0xf bank_mask:0xf
	v_mul_f32_e32 v246, v236, v232
	v_mul_f32_e32 v247, v236, v233
	v_exp_f32_e32 v246, v246
	v_exp_f32_e32 v247, v247
	s_nop 0
	v_pk_add_f32 v[246:247], v[246:247], v[238:239]
; __device__ __forceinline__ unsigned cvt_pk_bf16(float lo, float hi) { unsigned r; asm("v_cvt_pk_bf16_f32 %0, %1, %2" : "=v"(r) : "v"(lo), "v"(hi)); return r; }
; __device__ __forceinline__ float sigmoid_f(float v) { return __builtin_amdgcn_rcpf(1.0f + __builtin_amdgcn_exp2f(-1.4426950409f * v)); }
; __device__ __forceinline__ f32x4 bf4(u32x2 w) { return (f32x4){bf_lo(w.x), bf_hi(w.x), bf_lo(w.y), bf_hi(w.y)}; }
; __device__ __forceinline__ void phase10(const Args& a, int G, int wv, bool dummy = false) {
;     ...
;             for (int t = 0; t < 8; ++t) { const f32x4 gc = bf4(gr[t]), vc = bf4(vr[t]);
;                 const f32x4 gg = wg0 * gm2 + wg1 * gm1 + wg2 * gc + bg, vv = wv0 * vm2 + wv1 * vm1 + wv2 * vc + bv;
;                 f32x4 o;
; #pragma unroll
;                 for (int e = 0; e < 4; ++e) o[e] = gg[e] * pg8::sigmoid_f(gg[e]) * vv[e];
;                 u32x2 w; w.x = cvt_pk_bf16(o[0], o[1]); w.y = cvt_pk_bf16(o[2], o[3]);
;                 if (dummy) *(u32x2*)((bf16_t*)(a.ws + WS_D) + ((((size_t)(row0 + t0 + t)) * 5632 + ch) & (size_t)0x1ffffff)) = w; else *(u32x2*)(up + (size_t)(t0 + t) * 5632) = w;
;                 gm2 = gm1; gm1 = gc; vm2 = vm1; vm1 = vc; }
	v_rcp_f32_e32 v246, v246
	v_rcp_f32_e32 v247, v247
	v_pk_mul_f32 v[232:233], v[232:233], v[234:235]
	v_pk_mul_f32 v[232:233], v[232:233], v[246:247]
	v_cvt_pk_bf16_f32 v80, v232, v233
	v_pk_fma_f32 v[232:233], v[96:97], v[172:173], v[180:181]
	v_pk_fma_f32 v[234:235], v[84:85], v[204:205], v[212:213]
	s_nop 1
	v_fmac_f32_dpp v232, v96, v164 row_shr:1 row_mask:0xf bank_mask:0xf
	v_fmac_f32_dpp v233, v97, v165 row_shr:1 row_mask:0xf bank_mask:0xf
	v_fmac_f32_dpp v234, v84, v196 row_shr:1 row_mask:0xf bank_mask:0xf
	v_fmac_f32_dpp v235, v85, v197 row_shr:1 row_mask:0xf bank_mask:0xf
	v_fmac_f32_dpp v232, v96, v156 row_shr:2 row_mask:0xf bank_mask:0xf
	v_fmac_f32_dpp v233, v97, v157 row_shr:2 row_mask:0xf bank_mask:0xf
	v_fmac_f32_dpp v234, v84, v188 row_shr:2 row_mask:0xf bank_mask:0xf
	v_fmac_f32_dpp v235, v85, v189 row_shr:2 row_mask:0xf bank_mask:0xf
	v_fmac_f32_dpp v232, v112, v164 row_shl:15 row_mask:0xf bank_mask:0xf
	v_fmac_f32_dpp v233, v113, v165 row_shl:15 row_mask:0xf bank_mask:0xf
	v_fmac_f32_dpp v234, v100, v196 row_shl:15 row_mask:0xf bank_mask:0xf
	v_fmac_f32_dpp v235, v101, v197 row_shl:15 row_mask:0xf bank_mask:0xf
	v_fmac_f32_dpp v232, v112, v156 row_shl:14 row_mask:0xf bank_mask:0xf
	v_fmac_f32_dpp v233, v113, v157 row_shl:14 row_mask:0xf bank_mask:0xf
	v_fmac_f32_dpp v234, v100, v188 row_shl:14 row_mask:0xf bank_mask:0xf
	v_fmac_f32_dpp v235, v101, v189 row_shl:14 row_mask:0xf bank_mask:0xf
	v_mul_f32_e32 v246, v236, v232
	v_mul_f32_e32 v247, v236, v233
	v_exp_f32_e32 v246, v246
	v_exp_f32_e32 v247, v247
	s_nop 0
	v_pk_add_f32 v[246:247], v[246:247], v[238:239]
	v_rcp_f32_e32 v246, v246
	v_rcp_f32_e32 v247, v247
	v_pk_mul_f32 v[232:233], v[232:233], v[234:235]
	v_pk_mul_f32 v[232:233], v[232:233], v[246:247]
	v_cvt_pk_bf16_f32 v96, v232, v233
	v_pk_fma_f32 v[232:233], v[112:113], v[172:173], v[180:181]
	v_pk_fma_f32 v[234:235], v[100:101], v[204:205], v[212:213]
	s_nop 1
	v_fmac_f32_dpp v232, v112, v164 row_shr:1 row_mask:0xf bank_mask:0xf
	v_fmac_f32_dpp v233, v113, v165 row_shr:1 row_mask:0xf bank_mask:0xf
	v_fmac_f32_dpp v234, v100, v196 row_shr:1 row_mask:0xf bank_mask:0xf
	v_fmac_f32_dpp v235, v101, v197 row_shr:1 row_mask:0xf bank_mask:0xf
	v_fmac_f32_dpp v232, v112, v156 row_shr:2 row_mask:0xf bank_mask:0xf
	v_fmac_f32_dpp v233, v113, v157 row_shr:2 row_mask:0xf bank_mask:0xf
	v_fmac_f32_dpp v234, v100, v188 row_shr:2 row_mask:0xf bank_mask:0xf
	v_fmac_f32_dpp v235, v101, v189 row_shr:2 row_mask:0xf bank_mask:0xf
	v_fmac_f32_dpp v232, v124, v164 row_shl:15 row_mask:0xf bank_mask:0xf
	v_fmac_f32_dpp v233, v125, v165 row_shl:15 row_mask:0xf bank_mask:0xf
	v_fmac_f32_dpp v234, v116, v196 row_shl:15 row_mask:0xf bank_mask:0xf
	v_fmac_f32_dpp v235, v117, v197 row_shl:15 row_mask:0xf bank_mask:0xf
	v_fmac_f32_dpp v232, v124, v156 row_shl:14 row_mask:0xf bank_mask:0xf
	v_fmac_f32_dpp v233, v125, v157 row_shl:14 row_mask:0xf bank_mask:0xf
	v_fmac_f32_dpp v234, v116, v188 row_shl:14 row_mask:0xf bank_mask:0xf
	v_fmac_f32_dpp v235, v117, v189 row_shl:14 row_mask:0xf bank_mask:0xf
	v_mul_f32_e32 v246, v236, v232
	v_mul_f32_e32 v247, v236, v233
	v_exp_f32_e32 v246, v246
	v_exp_f32_e32 v247, v247
	s_nop 0
	v_pk_add_f32 v[246:247], v[246:247], v[238:239]
	v_rcp_f32_e32 v246, v246
	v_rcp_f32_e32 v247, v247
	v_pk_mul_f32 v[232:233], v[232:233], v[234:235]
	v_pk_mul_f32 v[232:233], v[232:233], v[246:247]
	v_cvt_pk_bf16_f32 v112, v232, v233
	v_pk_fma_f32 v[232:233], v[124:125], v[172:173], v[180:181]
	v_pk_fma_f32 v[234:235], v[116:117], v[204:205], v[212:213]
	s_nop 1
	v_fmac_f32_dpp v232, v124, v164 row_shr:1 row_mask:0xf bank_mask:0xf
	v_fmac_f32_dpp v233, v125, v165 row_shr:1 row_mask:0xf bank_mask:0xf
	v_fmac_f32_dpp v234, v116, v196 row_shr:1 row_mask:0xf bank_mask:0xf
	v_fmac_f32_dpp v235, v117, v197 row_shr:1 row_mask:0xf bank_mask:0xf
	v_fmac_f32_dpp v232, v124, v156 row_shr:2 row_mask:0xf bank_mask:0xf
	v_fmac_f32_dpp v233, v125, v157 row_shr:2 row_mask:0xf bank_mask:0xf
	v_fmac_f32_dpp v234, v116, v188 row_shr:2 row_mask:0xf bank_mask:0xf
	v_fmac_f32_dpp v235, v117, v189 row_shr:2 row_mask:0xf bank_mask:0xf
	v_mul_f32_e32 v246, v236, v232
	v_mul_f32_e32 v247, v236, v233
	v_exp_f32_e32 v246, v246
	v_exp_f32_e32 v247, v247
	s_nop 0
	v_pk_add_f32 v[246:247], v[246:247], v[238:239]
	v_rcp_f32_e32 v246, v246
	v_rcp_f32_e32 v247, v247
	v_pk_mul_f32 v[232:233], v[232:233], v[234:235]
	v_pk_mul_f32 v[232:233], v[232:233], v[246:247]
	v_cvt_pk_bf16_f32 v124, v232, v233
	v_pk_fma_f32 v[232:233], v[82:83], v[174:175], v[182:183]
	v_pk_fma_f32 v[234:235], v[70:71], v[206:207], v[214:215]
	s_nop 1
	v_fmac_f32_dpp v232, v82, v166 row_shr:1 row_mask:0xf bank_mask:0xf
	v_fmac_f32_dpp v233, v83, v167 row_shr:1 row_mask:0xf bank_mask:0xf
	v_fmac_f32_dpp v234, v70, v198 row_shr:1 row_mask:0xf bank_mask:0xf
	v_fmac_f32_dpp v235, v71, v199 row_shr:1 row_mask:0xf bank_mask:0xf
	v_fmac_f32_dpp v232, v82, v158 row_shr:2 row_mask:0xf bank_mask:0xf
	v_fmac_f32_dpp v233, v83, v159 row_shr:2 row_mask:0xf bank_mask:0xf
	v_fmac_f32_dpp v234, v70, v190 row_shr:2 row_mask:0xf bank_mask:0xf
	v_fmac_f32_dpp v235, v71, v191 row_shr:2 row_mask:0xf bank_mask:0xf
	v_fmac_f32_dpp v232, v98, v166 row_shl:15 row_mask:0xf bank_mask:0xf
	v_fmac_f32_dpp v233, v99, v167 row_shl:15 row_mask:0xf bank_mask:0xf
	v_fmac_f32_dpp v234, v86, v198 row_shl:15 row_mask:0xf bank_mask:0xf
	v_fmac_f32_dpp v235, v87, v199 row_shl:15 row_mask:0xf bank_mask:0xf
	v_fmac_f32_dpp v232, v98, v158 row_shl:14 row_mask:0xf bank_mask:0xf
	v_fmac_f32_dpp v233, v99, v159 row_shl:14 row_mask:0xf bank_mask:0xf
	v_fmac_f32_dpp v234, v86, v190 row_shl:14 row_mask:0xf bank_mask:0xf
; __device__ __forceinline__ unsigned cvt_pk_bf16(float lo, float hi) { unsigned r; asm("v_cvt_pk_bf16_f32 %0, %1, %2" : "=v"(r) : "v"(lo), "v"(hi)); return r; }
; __device__ __forceinline__ float sigmoid_f(float v) { return __builtin_amdgcn_rcpf(1.0f + __builtin_amdgcn_exp2f(-1.4426950409f * v)); }
; __device__ __forceinline__ f32x4 bf4(u32x2 w) { return (f32x4){bf_lo(w.x), bf_hi(w.x), bf_lo(w.y), bf_hi(w.y)}; }
; __device__ __forceinline__ void phase10(const Args& a, int G, int wv, bool dummy = false) {
;     ...
;             for (int t = 0; t < 8; ++t) { const f32x4 gc = bf4(gr[t]), vc = bf4(vr[t]);
;                 const f32x4 gg = wg0 * gm2 + wg1 * gm1 + wg2 * gc + bg, vv = wv0 * vm2 + wv1 * vm1 + wv2 * vc + bv;
;                 f32x4 o;
; #pragma unroll
;                 for (int e = 0; e < 4; ++e) o[e] = gg[e] * pg8::sigmoid_f(gg[e]) * vv[e];
;                 u32x2 w; w.x = cvt_pk_bf16(o[0], o[1]); w.y = cvt_pk_bf16(o[2], o[3]);
;                 if (dummy) *(u32x2*)((bf16_t*)(a.ws + WS_D) + ((((size_t)(row0 + t0 + t)) * 5632 + ch) & (size_t)0x1ffffff)) = w; else *(u32x2*)(up + (size_t)(t0 + t) * 5632) = w;
;                 gm2 = gm1; gm1 = gc; vm2 = vm1; vm1 = vc; }
	v_fmac_f32_dpp v235, v87, v191 row_shl:14 row_mask:0xf bank_mask:0xf
	v_mul_f32_e32 v246, v236, v232
	v_mul_f32_e32 v247, v236, v233
	v_exp_f32_e32 v246, v246
	v_exp_f32_e32 v247, v247
	s_nop 0
	v_pk_add_f32 v[246:247], v[246:247], v[238:239]
	v_rcp_f32_e32 v246, v246
	v_rcp_f32_e32 v247, v247
	v_pk_mul_f32 v[232:233], v[232:233], v[234:235]
	v_pk_mul_f32 v[232:233], v[232:233], v[246:247]
	v_cvt_pk_bf16_f32 v81, v232, v233
	v_pk_fma_f32 v[232:233], v[98:99], v[174:175], v[182:183]
	v_pk_fma_f32 v[234:235], v[86:87], v[206:207], v[214:215]
	s_nop 1
	v_fmac_f32_dpp v232, v98, v166 row_shr:1 row_mask:0xf bank_mask:0xf
	v_fmac_f32_dpp v233, v99, v167 row_shr:1 row_mask:0xf bank_mask:0xf
	v_fmac_f32_dpp v234, v86, v198 row_shr:1 row_mask:0xf bank_mask:0xf
	v_fmac_f32_dpp v235, v87, v199 row_shr:1 row_mask:0xf bank_mask:0xf
	v_fmac_f32_dpp v232, v98, v158 row_shr:2 row_mask:0xf bank_mask:0xf
	v_fmac_f32_dpp v233, v99, v159 row_shr:2 row_mask:0xf bank_mask:0xf
	v_fmac_f32_dpp v234, v86, v190 row_shr:2 row_mask:0xf bank_mask:0xf
	v_fmac_f32_dpp v235, v87, v191 row_shr:2 row_mask:0xf bank_mask:0xf
	v_fmac_f32_dpp v232, v114, v166 row_shl:15 row_mask:0xf bank_mask:0xf
	v_fmac_f32_dpp v233, v115, v167 row_shl:15 row_mask:0xf bank_mask:0xf
	v_fmac_f32_dpp v234, v102, v198 row_shl:15 row_mask:0xf bank_mask:0xf
	v_fmac_f32_dpp v235, v103, v199 row_shl:15 row_mask:0xf bank_mask:0xf
	v_fmac_f32_dpp v232, v114, v158 row_shl:14 row_mask:0xf bank_mask:0xf
	v_fmac_f32_dpp v233, v115, v159 row_shl:14 row_mask:0xf bank_mask:0xf
	v_fmac_f32_dpp v234, v102, v190 row_shl:14 row_mask:0xf bank_mask:0xf
	v_fmac_f32_dpp v235, v103, v191 row_shl:14 row_mask:0xf bank_mask:0xf
	v_mul_f32_e32 v246, v236, v232
	v_mul_f32_e32 v247, v236, v233
	v_exp_f32_e32 v246, v246
	v_exp_f32_e32 v247, v247
	s_nop 0
	v_pk_add_f32 v[246:247], v[246:247], v[238:239]
	v_rcp_f32_e32 v246, v246
	v_rcp_f32_e32 v247, v247
	v_pk_mul_f32 v[232:233], v[232:233], v[234:235]
	v_pk_mul_f32 v[232:233], v[232:233], v[246:247]
	v_cvt_pk_bf16_f32 v97, v232, v233
	v_pk_fma_f32 v[232:233], v[114:115], v[174:175], v[182:183]
	v_pk_fma_f32 v[234:235], v[102:103], v[206:207], v[214:215]
	s_nop 1
	v_fmac_f32_dpp v232, v114, v166 row_shr:1 row_mask:0xf bank_mask:0xf
	v_fmac_f32_dpp v233, v115, v167 row_shr:1 row_mask:0xf bank_mask:0xf
	v_fmac_f32_dpp v234, v102, v198 row_shr:1 row_mask:0xf bank_mask:0xf
	v_fmac_f32_dpp v235, v103, v199 row_shr:1 row_mask:0xf bank_mask:0xf
	v_fmac_f32_dpp v232, v114, v158 row_shr:2 row_mask:0xf bank_mask:0xf
	v_fmac_f32_dpp v233, v115, v159 row_shr:2 row_mask:0xf bank_mask:0xf
	v_fmac_f32_dpp v234, v102, v190 row_shr:2 row_mask:0xf bank_mask:0xf
	v_fmac_f32_dpp v235, v103, v191 row_shr:2 row_mask:0xf bank_mask:0xf
	v_fmac_f32_dpp v232, v126, v166 row_shl:15 row_mask:0xf bank_mask:0xf
	v_fmac_f32_dpp v233, v127, v167 row_shl:15 row_mask:0xf bank_mask:0xf
	v_fmac_f32_dpp v234, v118, v198 row_shl:15 row_mask:0xf bank_mask:0xf
	v_fmac_f32_dpp v235, v119, v199 row_shl:15 row_mask:0xf bank_mask:0xf
	v_fmac_f32_dpp v232, v126, v158 row_shl:14 row_mask:0xf bank_mask:0xf
	v_fmac_f32_dpp v233, v127, v159 row_shl:14 row_mask:0xf bank_mask:0xf
	v_fmac_f32_dpp v234, v118, v190 row_shl:14 row_mask:0xf bank_mask:0xf
	v_fmac_f32_dpp v235, v119, v191 row_shl:14 row_mask:0xf bank_mask:0xf
	v_mul_f32_e32 v246, v236, v232
	v_mul_f32_e32 v247, v236, v233
	v_exp_f32_e32 v246, v246
	v_exp_f32_e32 v247, v247
	s_nop 0
	v_pk_add_f32 v[246:247], v[246:247], v[238:239]
	v_rcp_f32_e32 v246, v246
	v_rcp_f32_e32 v247, v247
	v_pk_mul_f32 v[232:233], v[232:233], v[234:235]
	v_pk_mul_f32 v[232:233], v[232:233], v[246:247]
	v_cvt_pk_bf16_f32 v113, v232, v233
	v_pk_fma_f32 v[232:233], v[126:127], v[174:175], v[182:183]
	v_pk_fma_f32 v[234:235], v[118:119], v[206:207], v[214:215]
	s_nop 1
	v_fmac_f32_dpp v232, v126, v166 row_shr:1 row_mask:0xf bank_mask:0xf
	v_fmac_f32_dpp v233, v127, v167 row_shr:1 row_mask:0xf bank_mask:0xf
	v_fmac_f32_dpp v234, v118, v198 row_shr:1 row_mask:0xf bank_mask:0xf
	v_fmac_f32_dpp v235, v119, v199 row_shr:1 row_mask:0xf bank_mask:0xf
	v_fmac_f32_dpp v232, v126, v158 row_shr:2 row_mask:0xf bank_mask:0xf
	v_fmac_f32_dpp v233, v127, v159 row_shr:2 row_mask:0xf bank_mask:0xf
	v_fmac_f32_dpp v234, v118, v190 row_shr:2 row_mask:0xf bank_mask:0xf
	v_fmac_f32_dpp v235, v119, v191 row_shr:2 row_mask:0xf bank_mask:0xf
	v_mul_f32_e32 v246, v236, v232
	v_mul_f32_e32 v247, v236, v233
	v_exp_f32_e32 v246, v246
	v_exp_f32_e32 v247, v247
	s_nop 0
	v_pk_add_f32 v[246:247], v[246:247], v[238:239]
	v_rcp_f32_e32 v246, v246
	v_rcp_f32_e32 v247, v247
	v_pk_mul_f32 v[232:233], v[232:233], v[234:235]
	v_pk_mul_f32 v[232:233], v[232:233], v[246:247]
	v_cvt_pk_bf16_f32 v125, v232, v233
	v_pk_fma_f32 v[232:233], v[72:73], v[176:177], v[184:185]
	v_pk_fma_f32 v[234:235], v[64:65], v[208:209], v[216:217]
	s_nop 1
	v_fmac_f32_dpp v232, v72, v168 row_shr:1 row_mask:0xf bank_mask:0xf
	v_fmac_f32_dpp v233, v73, v169 row_shr:1 row_mask:0xf bank_mask:0xf
	v_fmac_f32_dpp v234, v64, v200 row_shr:1 row_mask:0xf bank_mask:0xf
	v_fmac_f32_dpp v235, v65, v201 row_shr:1 row_mask:0xf bank_mask:0xf
	v_fmac_f32_dpp v232, v72, v160 row_shr:2 row_mask:0xf bank_mask:0xf
	v_fmac_f32_dpp v233, v73, v161 row_shr:2 row_mask:0xf bank_mask:0xf
	v_fmac_f32_dpp v234, v64, v192 row_shr:2 row_mask:0xf bank_mask:0xf
	v_fmac_f32_dpp v235, v65, v193 row_shr:2 row_mask:0xf bank_mask:0xf
	v_fmac_f32_dpp v232, v88, v168 row_shl:15 row_mask:0xf bank_mask:0xf
	v_fmac_f32_dpp v233, v89, v169 row_shl:15 row_mask:0xf bank_mask:0xf
	v_fmac_f32_dpp v234, v76, v200 row_shl:15 row_mask:0xf bank_mask:0xf
	v_fmac_f32_dpp v235, v77, v201 row_shl:15 row_mask:0xf bank_mask:0xf
; __device__ __forceinline__ unsigned cvt_pk_bf16(float lo, float hi) { unsigned r; asm("v_cvt_pk_bf16_f32 %0, %1, %2" : "=v"(r) : "v"(lo), "v"(hi)); return r; }
; __device__ __forceinline__ float sigmoid_f(float v) { return __builtin_amdgcn_rcpf(1.0f + __builtin_amdgcn_exp2f(-1.4426950409f * v)); }
; __device__ __forceinline__ f32x4 bf4(u32x2 w) { return (f32x4){bf_lo(w.x), bf_hi(w.x), bf_lo(w.y), bf_hi(w.y)}; }
; __device__ __forceinline__ void phase10(const Args& a, int G, int wv, bool dummy = false) {
;     ...
;             for (int t = 0; t < 8; ++t) { const f32x4 gc = bf4(gr[t]), vc = bf4(vr[t]);
;                 const f32x4 gg = wg0 * gm2 + wg1 * gm1 + wg2 * gc + bg, vv = wv0 * vm2 + wv1 * vm1 + wv2 * vc + bv;
;                 f32x4 o;
; #pragma unroll
;                 for (int e = 0; e < 4; ++e) o[e] = gg[e] * pg8::sigmoid_f(gg[e]) * vv[e];
;                 u32x2 w; w.x = cvt_pk_bf16(o[0], o[1]); w.y = cvt_pk_bf16(o[2], o[3]);
;                 if (dummy) *(u32x2*)((bf16_t*)(a.ws + WS_D) + ((((size_t)(row0 + t0 + t)) * 5632 + ch) & (size_t)0x1ffffff)) = w; else *(u32x2*)(up + (size_t)(t0 + t) * 5632) = w;
;                 gm2 = gm1; gm1 = gc; vm2 = vm1; vm1 = vc; }
	v_fmac_f32_dpp v232, v88, v160 row_shl:14 row_mask:0xf bank_mask:0xf
	v_fmac_f32_dpp v233, v89, v161 row_shl:14 row_mask:0xf bank_mask:0xf
	v_fmac_f32_dpp v234, v76, v192 row_shl:14 row_mask:0xf bank_mask:0xf
	v_fmac_f32_dpp v235, v77, v193 row_shl:14 row_mask:0xf bank_mask:0xf
	v_mul_f32_e32 v246, v236, v232
	v_mul_f32_e32 v247, v236, v233
	v_exp_f32_e32 v246, v246
	v_exp_f32_e32 v247, v247
	s_nop 0
	v_pk_add_f32 v[246:247], v[246:247], v[238:239]
	v_rcp_f32_e32 v246, v246
	v_rcp_f32_e32 v247, v247
	v_pk_mul_f32 v[232:233], v[232:233], v[234:235]
	v_pk_mul_f32 v[232:233], v[232:233], v[246:247]
	v_cvt_pk_bf16_f32 v82, v232, v233
	v_pk_fma_f32 v[232:233], v[88:89], v[176:177], v[184:185]
	v_pk_fma_f32 v[234:235], v[76:77], v[208:209], v[216:217]
	s_nop 1
	v_fmac_f32_dpp v232, v88, v168 row_shr:1 row_mask:0xf bank_mask:0xf
	v_fmac_f32_dpp v233, v89, v169 row_shr:1 row_mask:0xf bank_mask:0xf
	v_fmac_f32_dpp v234, v76, v200 row_shr:1 row_mask:0xf bank_mask:0xf
	v_fmac_f32_dpp v235, v77, v201 row_shr:1 row_mask:0xf bank_mask:0xf
	v_fmac_f32_dpp v232, v88, v160 row_shr:2 row_mask:0xf bank_mask:0xf
	v_fmac_f32_dpp v233, v89, v161 row_shr:2 row_mask:0xf bank_mask:0xf
	v_fmac_f32_dpp v234, v76, v192 row_shr:2 row_mask:0xf bank_mask:0xf
	v_fmac_f32_dpp v235, v77, v193 row_shr:2 row_mask:0xf bank_mask:0xf
	v_fmac_f32_dpp v232, v104, v168 row_shl:15 row_mask:0xf bank_mask:0xf
	v_fmac_f32_dpp v233, v105, v169 row_shl:15 row_mask:0xf bank_mask:0xf
	v_fmac_f32_dpp v234, v92, v200 row_shl:15 row_mask:0xf bank_mask:0xf
	v_fmac_f32_dpp v235, v93, v201 row_shl:15 row_mask:0xf bank_mask:0xf
	v_fmac_f32_dpp v232, v104, v160 row_shl:14 row_mask:0xf bank_mask:0xf
	v_fmac_f32_dpp v233, v105, v161 row_shl:14 row_mask:0xf bank_mask:0xf
	v_fmac_f32_dpp v234, v92, v192 row_shl:14 row_mask:0xf bank_mask:0xf
	v_fmac_f32_dpp v235, v93, v193 row_shl:14 row_mask:0xf bank_mask:0xf
	v_mul_f32_e32 v246, v236, v232
	v_mul_f32_e32 v247, v236, v233
	v_exp_f32_e32 v246, v246
	v_exp_f32_e32 v247, v247
	s_nop 0
	v_pk_add_f32 v[246:247], v[246:247], v[238:239]
	v_rcp_f32_e32 v246, v246
	v_rcp_f32_e32 v247, v247
	v_pk_mul_f32 v[232:233], v[232:233], v[234:235]
	v_pk_mul_f32 v[232:233], v[232:233], v[246:247]
	v_cvt_pk_bf16_f32 v98, v232, v233
	v_pk_fma_f32 v[232:233], v[104:105], v[176:177], v[184:185]
	v_pk_fma_f32 v[234:235], v[92:93], v[208:209], v[216:217]
	s_nop 1
	v_fmac_f32_dpp v232, v104, v168 row_shr:1 row_mask:0xf bank_mask:0xf
	v_fmac_f32_dpp v233, v105, v169 row_shr:1 row_mask:0xf bank_mask:0xf
	v_fmac_f32_dpp v234, v92, v200 row_shr:1 row_mask:0xf bank_mask:0xf
	v_fmac_f32_dpp v235, v93, v201 row_shr:1 row_mask:0xf bank_mask:0xf
	v_fmac_f32_dpp v232, v104, v160 row_shr:2 row_mask:0xf bank_mask:0xf
	v_fmac_f32_dpp v233, v105, v161 row_shr:2 row_mask:0xf bank_mask:0xf
	v_fmac_f32_dpp v234, v92, v192 row_shr:2 row_mask:0xf bank_mask:0xf
	v_fmac_f32_dpp v235, v93, v193 row_shr:2 row_mask:0xf bank_mask:0xf
	v_fmac_f32_dpp v232, v120, v168 row_shl:15 row_mask:0xf bank_mask:0xf
	v_fmac_f32_dpp v233, v121, v169 row_shl:15 row_mask:0xf bank_mask:0xf
	v_fmac_f32_dpp v234, v108, v200 row_shl:15 row_mask:0xf bank_mask:0xf
	v_fmac_f32_dpp v235, v109, v201 row_shl:15 row_mask:0xf bank_mask:0xf
	v_fmac_f32_dpp v232, v120, v160 row_shl:14 row_mask:0xf bank_mask:0xf
	v_fmac_f32_dpp v233, v121, v161 row_shl:14 row_mask:0xf bank_mask:0xf
	v_fmac_f32_dpp v234, v108, v192 row_shl:14 row_mask:0xf bank_mask:0xf
	v_fmac_f32_dpp v235, v109, v193 row_shl:14 row_mask:0xf bank_mask:0xf
	v_mul_f32_e32 v246, v236, v232
	v_mul_f32_e32 v247, v236, v233
	v_exp_f32_e32 v246, v246
	v_exp_f32_e32 v247, v247
	s_nop 0
	v_pk_add_f32 v[246:247], v[246:247], v[238:239]
	v_rcp_f32_e32 v246, v246
	v_rcp_f32_e32 v247, v247
	v_pk_mul_f32 v[232:233], v[232:233], v[234:235]
	v_pk_mul_f32 v[232:233], v[232:233], v[246:247]
	v_cvt_pk_bf16_f32 v114, v232, v233
	v_pk_fma_f32 v[232:233], v[120:121], v[176:177], v[184:185]
	v_pk_fma_f32 v[234:235], v[108:109], v[208:209], v[216:217]
	s_nop 1
	v_fmac_f32_dpp v232, v120, v168 row_shr:1 row_mask:0xf bank_mask:0xf
	v_fmac_f32_dpp v233, v121, v169 row_shr:1 row_mask:0xf bank_mask:0xf
	v_fmac_f32_dpp v234, v108, v200 row_shr:1 row_mask:0xf bank_mask:0xf
	v_fmac_f32_dpp v235, v109, v201 row_shr:1 row_mask:0xf bank_mask:0xf
	v_fmac_f32_dpp v232, v120, v160 row_shr:2 row_mask:0xf bank_mask:0xf
	v_fmac_f32_dpp v233, v121, v161 row_shr:2 row_mask:0xf bank_mask:0xf
	v_fmac_f32_dpp v234, v108, v192 row_shr:2 row_mask:0xf bank_mask:0xf
	v_fmac_f32_dpp v235, v109, v193 row_shr:2 row_mask:0xf bank_mask:0xf
	v_mul_f32_e32 v246, v236, v232
	v_mul_f32_e32 v247, v236, v233
	v_exp_f32_e32 v246, v246
	v_exp_f32_e32 v247, v247
	s_nop 0
	v_pk_add_f32 v[246:247], v[246:247], v[238:239]
	v_rcp_f32_e32 v246, v246
	v_rcp_f32_e32 v247, v247
	v_pk_mul_f32 v[232:233], v[232:233], v[234:235]
	v_pk_mul_f32 v[232:233], v[232:233], v[246:247]
	v_cvt_pk_bf16_f32 v126, v232, v233
	v_pk_fma_f32 v[232:233], v[74:75], v[178:179], v[186:187]
	v_pk_fma_f32 v[234:235], v[66:67], v[210:211], v[218:219]
	s_nop 1
	v_fmac_f32_dpp v232, v74, v170 row_shr:1 row_mask:0xf bank_mask:0xf
	v_fmac_f32_dpp v233, v75, v171 row_shr:1 row_mask:0xf bank_mask:0xf
	v_fmac_f32_dpp v234, v66, v202 row_shr:1 row_mask:0xf bank_mask:0xf
	v_fmac_f32_dpp v235, v67, v203 row_shr:1 row_mask:0xf bank_mask:0xf
	v_fmac_f32_dpp v232, v74, v162 row_shr:2 row_mask:0xf bank_mask:0xf
	v_fmac_f32_dpp v233, v75, v163 row_shr:2 row_mask:0xf bank_mask:0xf
	v_fmac_f32_dpp v234, v66, v194 row_shr:2 row_mask:0xf bank_mask:0xf
	v_fmac_f32_dpp v235, v67, v195 row_shr:2 row_mask:0xf bank_mask:0xf
	v_fmac_f32_dpp v232, v90, v170 row_shl:15 row_mask:0xf bank_mask:0xf
; __device__ __forceinline__ unsigned cvt_pk_bf16(float lo, float hi) { unsigned r; asm("v_cvt_pk_bf16_f32 %0, %1, %2" : "=v"(r) : "v"(lo), "v"(hi)); return r; }
; __device__ __forceinline__ float sigmoid_f(float v) { return __builtin_amdgcn_rcpf(1.0f + __builtin_amdgcn_exp2f(-1.4426950409f * v)); }
; __device__ __forceinline__ u32x4 pack8(f32x4 a, f32x4 b) { u32x4 w; w.x = cvt_pk_bf16(a[0], a[1]); w.y = cvt_pk_bf16(a[2], a[3]); w.z = cvt_pk_bf16(b[0], b[1]); w.w = cvt_pk_bf16(b[2], b[3]); return w; }
; __device__ __forceinline__ f32x4 bf4(u32x2 w) { return (f32x4){bf_lo(w.x), bf_hi(w.x), bf_lo(w.y), bf_hi(w.y)}; }
;     __device__ __forceinline__ void operator()(const f32x4 (&acc)[2][2][4][2], const Unit& u, int wr, int wc, int fr, int fq) const {
;     ...
;             for (int m = 0; m < 4; ++m) { const int row = row0 + ai * HALF + m * 16; bf16_t* rowp = UP + (size_t)row * 5632 + u.pn * HALF + wc * 32 + 8 * fq;
; #pragma unroll
;                 for (int bj = 0; bj < 2; ++bj) { const u32x4 w = pack8(acc[ai][bj][m][0], acc[ai][bj][m][1]); __builtin_nontemporal_store(w, (u32x4*)(rowp + (size_t)bj * ((size_t)16384 * 5632)));
; __device__ __forceinline__ void phase10(const Args& a, int G, int wv, bool dummy = false) {
;     ...
;             for (int t = 0; t < 8; ++t) { const f32x4 gc = bf4(gr[t]), vc = bf4(vr[t]);
;                 const f32x4 gg = wg0 * gm2 + wg1 * gm1 + wg2 * gc + bg, vv = wv0 * vm2 + wv1 * vm1 + wv2 * vc + bv;
;                 f32x4 o;
; #pragma unroll
;                 for (int e = 0; e < 4; ++e) o[e] = gg[e] * pg8::sigmoid_f(gg[e]) * vv[e];
;                 u32x2 w; w.x = cvt_pk_bf16(o[0], o[1]); w.y = cvt_pk_bf16(o[2], o[3]);
;                 if (dummy) *(u32x2*)((bf16_t*)(a.ws + WS_D) + ((((size_t)(row0 + t0 + t)) * 5632 + ch) & (size_t)0x1ffffff)) = w; else *(u32x2*)(up + (size_t)(t0 + t) * 5632) = w;
;                 gm2 = gm1; gm1 = gc; vm2 = vm1; vm1 = vc; }
	v_fmac_f32_dpp v233, v91, v171 row_shl:15 row_mask:0xf bank_mask:0xf
	v_fmac_f32_dpp v234, v78, v202 row_shl:15 row_mask:0xf bank_mask:0xf
	v_fmac_f32_dpp v235, v79, v203 row_shl:15 row_mask:0xf bank_mask:0xf
	v_fmac_f32_dpp v232, v90, v162 row_shl:14 row_mask:0xf bank_mask:0xf
	v_fmac_f32_dpp v233, v91, v163 row_shl:14 row_mask:0xf bank_mask:0xf
	v_fmac_f32_dpp v234, v78, v194 row_shl:14 row_mask:0xf bank_mask:0xf
	v_fmac_f32_dpp v235, v79, v195 row_shl:14 row_mask:0xf bank_mask:0xf
	v_mul_f32_e32 v246, v236, v232
	v_mul_f32_e32 v247, v236, v233
	v_exp_f32_e32 v246, v246
	v_exp_f32_e32 v247, v247
	s_nop 0
	v_pk_add_f32 v[246:247], v[246:247], v[238:239]
	v_rcp_f32_e32 v246, v246
	v_rcp_f32_e32 v247, v247
	v_pk_mul_f32 v[232:233], v[232:233], v[234:235]
	v_pk_mul_f32 v[232:233], v[232:233], v[246:247]
	v_cvt_pk_bf16_f32 v83, v232, v233
	v_pk_fma_f32 v[232:233], v[90:91], v[178:179], v[186:187]
	v_pk_fma_f32 v[234:235], v[78:79], v[210:211], v[218:219]
	s_nop 1
	v_fmac_f32_dpp v232, v90, v170 row_shr:1 row_mask:0xf bank_mask:0xf
	v_fmac_f32_dpp v233, v91, v171 row_shr:1 row_mask:0xf bank_mask:0xf
	v_fmac_f32_dpp v234, v78, v202 row_shr:1 row_mask:0xf bank_mask:0xf
	v_fmac_f32_dpp v235, v79, v203 row_shr:1 row_mask:0xf bank_mask:0xf
	v_fmac_f32_dpp v232, v90, v162 row_shr:2 row_mask:0xf bank_mask:0xf
	v_fmac_f32_dpp v233, v91, v163 row_shr:2 row_mask:0xf bank_mask:0xf
	v_fmac_f32_dpp v234, v78, v194 row_shr:2 row_mask:0xf bank_mask:0xf
	v_fmac_f32_dpp v235, v79, v195 row_shr:2 row_mask:0xf bank_mask:0xf
	v_fmac_f32_dpp v232, v106, v170 row_shl:15 row_mask:0xf bank_mask:0xf
	v_fmac_f32_dpp v233, v107, v171 row_shl:15 row_mask:0xf bank_mask:0xf
	v_fmac_f32_dpp v234, v94, v202 row_shl:15 row_mask:0xf bank_mask:0xf
	v_fmac_f32_dpp v235, v95, v203 row_shl:15 row_mask:0xf bank_mask:0xf
	v_fmac_f32_dpp v232, v106, v162 row_shl:14 row_mask:0xf bank_mask:0xf
	v_fmac_f32_dpp v233, v107, v163 row_shl:14 row_mask:0xf bank_mask:0xf
	v_fmac_f32_dpp v234, v94, v194 row_shl:14 row_mask:0xf bank_mask:0xf
	v_fmac_f32_dpp v235, v95, v195 row_shl:14 row_mask:0xf bank_mask:0xf
	v_mul_f32_e32 v246, v236, v232
	v_mul_f32_e32 v247, v236, v233
	v_exp_f32_e32 v246, v246
	v_exp_f32_e32 v247, v247
	s_nop 0
	v_pk_add_f32 v[246:247], v[246:247], v[238:239]
	v_rcp_f32_e32 v246, v246
	v_rcp_f32_e32 v247, v247
	v_pk_mul_f32 v[232:233], v[232:233], v[234:235]
	v_pk_mul_f32 v[232:233], v[232:233], v[246:247]
	v_cvt_pk_bf16_f32 v99, v232, v233
	v_pk_fma_f32 v[232:233], v[106:107], v[178:179], v[186:187]
	v_pk_fma_f32 v[234:235], v[94:95], v[210:211], v[218:219]
	s_nop 1
	v_fmac_f32_dpp v232, v106, v170 row_shr:1 row_mask:0xf bank_mask:0xf
	v_fmac_f32_dpp v233, v107, v171 row_shr:1 row_mask:0xf bank_mask:0xf
	v_fmac_f32_dpp v234, v94, v202 row_shr:1 row_mask:0xf bank_mask:0xf
	v_fmac_f32_dpp v235, v95, v203 row_shr:1 row_mask:0xf bank_mask:0xf
	v_fmac_f32_dpp v232, v106, v162 row_shr:2 row_mask:0xf bank_mask:0xf
	v_fmac_f32_dpp v233, v107, v163 row_shr:2 row_mask:0xf bank_mask:0xf
	v_fmac_f32_dpp v234, v94, v194 row_shr:2 row_mask:0xf bank_mask:0xf
	v_fmac_f32_dpp v235, v95, v195 row_shr:2 row_mask:0xf bank_mask:0xf
	v_fmac_f32_dpp v232, v122, v170 row_shl:15 row_mask:0xf bank_mask:0xf
	v_fmac_f32_dpp v233, v123, v171 row_shl:15 row_mask:0xf bank_mask:0xf
	v_fmac_f32_dpp v234, v110, v202 row_shl:15 row_mask:0xf bank_mask:0xf
	v_fmac_f32_dpp v235, v111, v203 row_shl:15 row_mask:0xf bank_mask:0xf
	v_fmac_f32_dpp v232, v122, v162 row_shl:14 row_mask:0xf bank_mask:0xf
	v_fmac_f32_dpp v233, v123, v163 row_shl:14 row_mask:0xf bank_mask:0xf
	v_fmac_f32_dpp v234, v110, v194 row_shl:14 row_mask:0xf bank_mask:0xf
	v_fmac_f32_dpp v235, v111, v195 row_shl:14 row_mask:0xf bank_mask:0xf
	v_mul_f32_e32 v246, v236, v232
	v_mul_f32_e32 v247, v236, v233
	v_exp_f32_e32 v246, v246
	v_exp_f32_e32 v247, v247
	s_nop 0
	v_pk_add_f32 v[246:247], v[246:247], v[238:239]
	v_rcp_f32_e32 v246, v246
	v_rcp_f32_e32 v247, v247
	v_pk_mul_f32 v[232:233], v[232:233], v[234:235]
	v_pk_mul_f32 v[232:233], v[232:233], v[246:247]
	v_cvt_pk_bf16_f32 v115, v232, v233
	v_pk_fma_f32 v[232:233], v[122:123], v[178:179], v[186:187]
	v_pk_fma_f32 v[234:235], v[110:111], v[210:211], v[218:219]
	s_nop 1
	v_fmac_f32_dpp v232, v122, v170 row_shr:1 row_mask:0xf bank_mask:0xf
	v_fmac_f32_dpp v233, v123, v171 row_shr:1 row_mask:0xf bank_mask:0xf
	v_fmac_f32_dpp v234, v110, v202 row_shr:1 row_mask:0xf bank_mask:0xf
	v_fmac_f32_dpp v235, v111, v203 row_shr:1 row_mask:0xf bank_mask:0xf
	v_fmac_f32_dpp v232, v122, v162 row_shr:2 row_mask:0xf bank_mask:0xf
	v_fmac_f32_dpp v233, v123, v163 row_shr:2 row_mask:0xf bank_mask:0xf
	v_fmac_f32_dpp v234, v110, v194 row_shr:2 row_mask:0xf bank_mask:0xf
	v_fmac_f32_dpp v235, v111, v195 row_shr:2 row_mask:0xf bank_mask:0xf
	v_mul_f32_e32 v246, v236, v232
	v_mul_f32_e32 v247, v236, v233
	v_exp_f32_e32 v246, v246
	v_exp_f32_e32 v247, v247
	s_nop 0
	v_pk_add_f32 v[246:247], v[246:247], v[238:239]
	v_rcp_f32_e32 v246, v246
	v_rcp_f32_e32 v247, v247
	v_pk_mul_f32 v[232:233], v[232:233], v[234:235]
	v_pk_mul_f32 v[232:233], v[232:233], v[246:247]
	v_cvt_pk_bf16_f32 v127, v232, v233
	s_andn2_b64 exec, exec, s[64:65]
	global_store_dwordx4 v149, v[124:127], s[100:101]
	s_mov_b64 exec, -1
	s_add_u32 s36, s100, 0x2c000
	s_addc_u32 s37, s101, 0
	global_store_dwordx4 v149, v[112:115], s[36:37]
	s_add_u32 s36, s100, 0x58000
	s_addc_u32 s37, s101, 0
	global_store_dwordx4 v149, v[96:99], s[36:37]
	s_add_u32 s36, s100, 0x84000
	s_addc_u32 s37, s101, 0
	global_store_dwordx4 v149, v[80:83], s[36:37]
	s_nop 4
	v_pk_fma_f32 v[232:233], v[16:17], v[172:173], v[180:181]
	v_pk_fma_f32 v[234:235], v[4:5], v[204:205], v[212:213]
; __device__ __forceinline__ unsigned cvt_pk_bf16(float lo, float hi) { unsigned r; asm("v_cvt_pk_bf16_f32 %0, %1, %2" : "=v"(r) : "v"(lo), "v"(hi)); return r; }
; __device__ __forceinline__ float sigmoid_f(float v) { return __builtin_amdgcn_rcpf(1.0f + __builtin_amdgcn_exp2f(-1.4426950409f * v)); }
; __device__ __forceinline__ f32x4 bf4(u32x2 w) { return (f32x4){bf_lo(w.x), bf_hi(w.x), bf_lo(w.y), bf_hi(w.y)}; }
; __device__ __forceinline__ void phase10(const Args& a, int G, int wv, bool dummy = false) {
;     ...
;             for (int t = 0; t < 8; ++t) { const f32x4 gc = bf4(gr[t]), vc = bf4(vr[t]);
;                 const f32x4 gg = wg0 * gm2 + wg1 * gm1 + wg2 * gc + bg, vv = wv0 * vm2 + wv1 * vm1 + wv2 * vc + bv;
;                 f32x4 o;
; #pragma unroll
;                 for (int e = 0; e < 4; ++e) o[e] = gg[e] * pg8::sigmoid_f(gg[e]) * vv[e];
;                 u32x2 w; w.x = cvt_pk_bf16(o[0], o[1]); w.y = cvt_pk_bf16(o[2], o[3]);
;                 if (dummy) *(u32x2*)((bf16_t*)(a.ws + WS_D) + ((((size_t)(row0 + t0 + t)) * 5632 + ch) & (size_t)0x1ffffff)) = w; else *(u32x2*)(up + (size_t)(t0 + t) * 5632) = w;
;                 gm2 = gm1; gm1 = gc; vm2 = vm1; vm1 = vc; }
	s_nop 1
	v_fmac_f32_dpp v232, v16, v164 row_shr:1 row_mask:0xf bank_mask:0xf
	v_fmac_f32_dpp v233, v17, v165 row_shr:1 row_mask:0xf bank_mask:0xf
	v_fmac_f32_dpp v234, v4, v196 row_shr:1 row_mask:0xf bank_mask:0xf
	v_fmac_f32_dpp v235, v5, v197 row_shr:1 row_mask:0xf bank_mask:0xf
	v_fmac_f32_dpp v232, v16, v156 row_shr:2 row_mask:0xf bank_mask:0xf
	v_fmac_f32_dpp v233, v17, v157 row_shr:2 row_mask:0xf bank_mask:0xf
	v_fmac_f32_dpp v234, v4, v188 row_shr:2 row_mask:0xf bank_mask:0xf
	v_fmac_f32_dpp v235, v5, v189 row_shr:2 row_mask:0xf bank_mask:0xf
	v_fmac_f32_dpp v232, v32, v164 row_shl:15 row_mask:0xf bank_mask:0xf
	v_fmac_f32_dpp v233, v33, v165 row_shl:15 row_mask:0xf bank_mask:0xf
	v_fmac_f32_dpp v234, v20, v196 row_shl:15 row_mask:0xf bank_mask:0xf
	v_fmac_f32_dpp v235, v21, v197 row_shl:15 row_mask:0xf bank_mask:0xf
	v_fmac_f32_dpp v232, v32, v156 row_shl:14 row_mask:0xf bank_mask:0xf
	v_fmac_f32_dpp v233, v33, v157 row_shl:14 row_mask:0xf bank_mask:0xf
	v_fmac_f32_dpp v234, v20, v188 row_shl:14 row_mask:0xf bank_mask:0xf
	v_fmac_f32_dpp v235, v21, v189 row_shl:14 row_mask:0xf bank_mask:0xf
	v_mul_f32_e32 v246, v236, v232
	v_mul_f32_e32 v247, v236, v233
	v_exp_f32_e32 v246, v246
	v_exp_f32_e32 v247, v247
	s_nop 0
	v_pk_add_f32 v[246:247], v[246:247], v[238:239]
	v_rcp_f32_e32 v246, v246
	v_rcp_f32_e32 v247, v247
	v_pk_mul_f32 v[232:233], v[232:233], v[234:235]
	v_pk_mul_f32 v[232:233], v[232:233], v[246:247]
	v_cvt_pk_bf16_f32 v16, v232, v233
	v_pk_fma_f32 v[232:233], v[32:33], v[172:173], v[180:181]
	v_pk_fma_f32 v[234:235], v[20:21], v[204:205], v[212:213]
	s_nop 1
	v_fmac_f32_dpp v232, v32, v164 row_shr:1 row_mask:0xf bank_mask:0xf
	v_fmac_f32_dpp v233, v33, v165 row_shr:1 row_mask:0xf bank_mask:0xf
	v_fmac_f32_dpp v234, v20, v196 row_shr:1 row_mask:0xf bank_mask:0xf
	v_fmac_f32_dpp v235, v21, v197 row_shr:1 row_mask:0xf bank_mask:0xf
	v_fmac_f32_dpp v232, v32, v156 row_shr:2 row_mask:0xf bank_mask:0xf
	v_fmac_f32_dpp v233, v33, v157 row_shr:2 row_mask:0xf bank_mask:0xf
	v_fmac_f32_dpp v234, v20, v188 row_shr:2 row_mask:0xf bank_mask:0xf
	v_fmac_f32_dpp v235, v21, v189 row_shr:2 row_mask:0xf bank_mask:0xf
	v_fmac_f32_dpp v232, v48, v164 row_shl:15 row_mask:0xf bank_mask:0xf
	v_fmac_f32_dpp v233, v49, v165 row_shl:15 row_mask:0xf bank_mask:0xf
	v_fmac_f32_dpp v234, v36, v196 row_shl:15 row_mask:0xf bank_mask:0xf
	v_fmac_f32_dpp v235, v37, v197 row_shl:15 row_mask:0xf bank_mask:0xf
	v_fmac_f32_dpp v232, v48, v156 row_shl:14 row_mask:0xf bank_mask:0xf
	v_fmac_f32_dpp v233, v49, v157 row_shl:14 row_mask:0xf bank_mask:0xf
	v_fmac_f32_dpp v234, v36, v188 row_shl:14 row_mask:0xf bank_mask:0xf
	v_fmac_f32_dpp v235, v37, v189 row_shl:14 row_mask:0xf bank_mask:0xf
	v_mul_f32_e32 v246, v236, v232
	v_mul_f32_e32 v247, v236, v233
	v_exp_f32_e32 v246, v246
	v_exp_f32_e32 v247, v247
	s_nop 0
	v_pk_add_f32 v[246:247], v[246:247], v[238:239]
	v_rcp_f32_e32 v246, v246
	v_rcp_f32_e32 v247, v247
	v_pk_mul_f32 v[232:233], v[232:233], v[234:235]
	v_pk_mul_f32 v[232:233], v[232:233], v[246:247]
	v_cvt_pk_bf16_f32 v32, v232, v233
	v_pk_fma_f32 v[232:233], v[48:49], v[172:173], v[180:181]
	v_pk_fma_f32 v[234:235], v[36:37], v[204:205], v[212:213]
	s_nop 1
	v_fmac_f32_dpp v232, v48, v164 row_shr:1 row_mask:0xf bank_mask:0xf
	v_fmac_f32_dpp v233, v49, v165 row_shr:1 row_mask:0xf bank_mask:0xf
	v_fmac_f32_dpp v234, v36, v196 row_shr:1 row_mask:0xf bank_mask:0xf
	v_fmac_f32_dpp v235, v37, v197 row_shr:1 row_mask:0xf bank_mask:0xf
	v_fmac_f32_dpp v232, v48, v156 row_shr:2 row_mask:0xf bank_mask:0xf
	v_fmac_f32_dpp v233, v49, v157 row_shr:2 row_mask:0xf bank_mask:0xf
	v_fmac_f32_dpp v234, v36, v188 row_shr:2 row_mask:0xf bank_mask:0xf
	v_fmac_f32_dpp v235, v37, v189 row_shr:2 row_mask:0xf bank_mask:0xf
	v_fmac_f32_dpp v232, v60, v164 row_shl:15 row_mask:0xf bank_mask:0xf
	v_fmac_f32_dpp v233, v61, v165 row_shl:15 row_mask:0xf bank_mask:0xf
	v_fmac_f32_dpp v234, v52, v196 row_shl:15 row_mask:0xf bank_mask:0xf
	v_fmac_f32_dpp v235, v53, v197 row_shl:15 row_mask:0xf bank_mask:0xf
	v_fmac_f32_dpp v232, v60, v156 row_shl:14 row_mask:0xf bank_mask:0xf
	v_fmac_f32_dpp v233, v61, v157 row_shl:14 row_mask:0xf bank_mask:0xf
	v_fmac_f32_dpp v234, v52, v188 row_shl:14 row_mask:0xf bank_mask:0xf
	v_fmac_f32_dpp v235, v53, v189 row_shl:14 row_mask:0xf bank_mask:0xf
	v_mul_f32_e32 v246, v236, v232
	v_mul_f32_e32 v247, v236, v233
	v_exp_f32_e32 v246, v246
	v_exp_f32_e32 v247, v247
	s_nop 0
	v_pk_add_f32 v[246:247], v[246:247], v[238:239]
	v_rcp_f32_e32 v246, v246
	v_rcp_f32_e32 v247, v247
	v_pk_mul_f32 v[232:233], v[232:233], v[234:235]
	v_pk_mul_f32 v[232:233], v[232:233], v[246:247]
	v_cvt_pk_bf16_f32 v48, v232, v233
	v_pk_fma_f32 v[232:233], v[60:61], v[172:173], v[180:181]
	v_pk_fma_f32 v[234:235], v[52:53], v[204:205], v[212:213]
	s_nop 1
	v_fmac_f32_dpp v232, v60, v164 row_shr:1 row_mask:0xf bank_mask:0xf
	v_fmac_f32_dpp v233, v61, v165 row_shr:1 row_mask:0xf bank_mask:0xf
	v_fmac_f32_dpp v234, v52, v196 row_shr:1 row_mask:0xf bank_mask:0xf
	v_fmac_f32_dpp v235, v53, v197 row_shr:1 row_mask:0xf bank_mask:0xf
	v_fmac_f32_dpp v232, v60, v156 row_shr:2 row_mask:0xf bank_mask:0xf
	v_fmac_f32_dpp v233, v61, v157 row_shr:2 row_mask:0xf bank_mask:0xf
	v_fmac_f32_dpp v234, v52, v188 row_shr:2 row_mask:0xf bank_mask:0xf
	v_fmac_f32_dpp v235, v53, v189 row_shr:2 row_mask:0xf bank_mask:0xf
	v_mul_f32_e32 v246, v236, v232
	v_mul_f32_e32 v247, v236, v233
	v_exp_f32_e32 v246, v246
	v_exp_f32_e32 v247, v247
	s_nop 0
	v_pk_add_f32 v[246:247], v[246:247], v[238:239]
	v_rcp_f32_e32 v246, v246
	v_rcp_f32_e32 v247, v247
	v_pk_mul_f32 v[232:233], v[232:233], v[234:235]
; __device__ __forceinline__ unsigned cvt_pk_bf16(float lo, float hi) { unsigned r; asm("v_cvt_pk_bf16_f32 %0, %1, %2" : "=v"(r) : "v"(lo), "v"(hi)); return r; }
; __device__ __forceinline__ float sigmoid_f(float v) { return __builtin_amdgcn_rcpf(1.0f + __builtin_amdgcn_exp2f(-1.4426950409f * v)); }
; __device__ __forceinline__ f32x4 bf4(u32x2 w) { return (f32x4){bf_lo(w.x), bf_hi(w.x), bf_lo(w.y), bf_hi(w.y)}; }
; __device__ __forceinline__ void phase10(const Args& a, int G, int wv, bool dummy = false) {
;     ...
;             for (int t = 0; t < 8; ++t) { const f32x4 gc = bf4(gr[t]), vc = bf4(vr[t]);
;                 const f32x4 gg = wg0 * gm2 + wg1 * gm1 + wg2 * gc + bg, vv = wv0 * vm2 + wv1 * vm1 + wv2 * vc + bv;
;                 f32x4 o;
; #pragma unroll
;                 for (int e = 0; e < 4; ++e) o[e] = gg[e] * pg8::sigmoid_f(gg[e]) * vv[e];
;                 u32x2 w; w.x = cvt_pk_bf16(o[0], o[1]); w.y = cvt_pk_bf16(o[2], o[3]);
;                 if (dummy) *(u32x2*)((bf16_t*)(a.ws + WS_D) + ((((size_t)(row0 + t0 + t)) * 5632 + ch) & (size_t)0x1ffffff)) = w; else *(u32x2*)(up + (size_t)(t0 + t) * 5632) = w;
;                 gm2 = gm1; gm1 = gc; vm2 = vm1; vm1 = vc; }
	v_pk_mul_f32 v[232:233], v[232:233], v[246:247]
	v_cvt_pk_bf16_f32 v60, v232, v233
	v_pk_fma_f32 v[232:233], v[18:19], v[174:175], v[182:183]
	v_pk_fma_f32 v[234:235], v[6:7], v[206:207], v[214:215]
	s_nop 1
	v_fmac_f32_dpp v232, v18, v166 row_shr:1 row_mask:0xf bank_mask:0xf
	v_fmac_f32_dpp v233, v19, v167 row_shr:1 row_mask:0xf bank_mask:0xf
	v_fmac_f32_dpp v234, v6, v198 row_shr:1 row_mask:0xf bank_mask:0xf
	v_fmac_f32_dpp v235, v7, v199 row_shr:1 row_mask:0xf bank_mask:0xf
	v_fmac_f32_dpp v232, v18, v158 row_shr:2 row_mask:0xf bank_mask:0xf
	v_fmac_f32_dpp v233, v19, v159 row_shr:2 row_mask:0xf bank_mask:0xf
	v_fmac_f32_dpp v234, v6, v190 row_shr:2 row_mask:0xf bank_mask:0xf
	v_fmac_f32_dpp v235, v7, v191 row_shr:2 row_mask:0xf bank_mask:0xf
	v_fmac_f32_dpp v232, v34, v166 row_shl:15 row_mask:0xf bank_mask:0xf
	v_fmac_f32_dpp v233, v35, v167 row_shl:15 row_mask:0xf bank_mask:0xf
	v_fmac_f32_dpp v234, v22, v198 row_shl:15 row_mask:0xf bank_mask:0xf
	v_fmac_f32_dpp v235, v23, v199 row_shl:15 row_mask:0xf bank_mask:0xf
	v_fmac_f32_dpp v232, v34, v158 row_shl:14 row_mask:0xf bank_mask:0xf
	v_fmac_f32_dpp v233, v35, v159 row_shl:14 row_mask:0xf bank_mask:0xf
	v_fmac_f32_dpp v234, v22, v190 row_shl:14 row_mask:0xf bank_mask:0xf
	v_fmac_f32_dpp v235, v23, v191 row_shl:14 row_mask:0xf bank_mask:0xf
	v_mul_f32_e32 v246, v236, v232
	v_mul_f32_e32 v247, v236, v233
	v_exp_f32_e32 v246, v246
	v_exp_f32_e32 v247, v247
	s_nop 0
	v_pk_add_f32 v[246:247], v[246:247], v[238:239]
	v_rcp_f32_e32 v246, v246
	v_rcp_f32_e32 v247, v247
	v_pk_mul_f32 v[232:233], v[232:233], v[234:235]
	v_pk_mul_f32 v[232:233], v[232:233], v[246:247]
	v_cvt_pk_bf16_f32 v17, v232, v233
	v_pk_fma_f32 v[232:233], v[34:35], v[174:175], v[182:183]
	v_pk_fma_f32 v[234:235], v[22:23], v[206:207], v[214:215]
	s_nop 1
	v_fmac_f32_dpp v232, v34, v166 row_shr:1 row_mask:0xf bank_mask:0xf
	v_fmac_f32_dpp v233, v35, v167 row_shr:1 row_mask:0xf bank_mask:0xf
	v_fmac_f32_dpp v234, v22, v198 row_shr:1 row_mask:0xf bank_mask:0xf
	v_fmac_f32_dpp v235, v23, v199 row_shr:1 row_mask:0xf bank_mask:0xf
	v_fmac_f32_dpp v232, v34, v158 row_shr:2 row_mask:0xf bank_mask:0xf
	v_fmac_f32_dpp v233, v35, v159 row_shr:2 row_mask:0xf bank_mask:0xf
	v_fmac_f32_dpp v234, v22, v190 row_shr:2 row_mask:0xf bank_mask:0xf
	v_fmac_f32_dpp v235, v23, v191 row_shr:2 row_mask:0xf bank_mask:0xf
	v_fmac_f32_dpp v232, v50, v166 row_shl:15 row_mask:0xf bank_mask:0xf
	v_fmac_f32_dpp v233, v51, v167 row_shl:15 row_mask:0xf bank_mask:0xf
	v_fmac_f32_dpp v234, v38, v198 row_shl:15 row_mask:0xf bank_mask:0xf
	v_fmac_f32_dpp v235, v39, v199 row_shl:15 row_mask:0xf bank_mask:0xf
	v_fmac_f32_dpp v232, v50, v158 row_shl:14 row_mask:0xf bank_mask:0xf
	v_fmac_f32_dpp v233, v51, v159 row_shl:14 row_mask:0xf bank_mask:0xf
	v_fmac_f32_dpp v234, v38, v190 row_shl:14 row_mask:0xf bank_mask:0xf
	v_fmac_f32_dpp v235, v39, v191 row_shl:14 row_mask:0xf bank_mask:0xf
	v_mul_f32_e32 v246, v236, v232
	v_mul_f32_e32 v247, v236, v233
	v_exp_f32_e32 v246, v246
	v_exp_f32_e32 v247, v247
	s_nop 0
	v_pk_add_f32 v[246:247], v[246:247], v[238:239]
	v_rcp_f32_e32 v246, v246
	v_rcp_f32_e32 v247, v247
	v_pk_mul_f32 v[232:233], v[232:233], v[234:235]
	v_pk_mul_f32 v[232:233], v[232:233], v[246:247]
	v_cvt_pk_bf16_f32 v33, v232, v233
	v_pk_fma_f32 v[232:233], v[50:51], v[174:175], v[182:183]
	v_pk_fma_f32 v[234:235], v[38:39], v[206:207], v[214:215]
	s_nop 1
	v_fmac_f32_dpp v232, v50, v166 row_shr:1 row_mask:0xf bank_mask:0xf
	v_fmac_f32_dpp v233, v51, v167 row_shr:1 row_mask:0xf bank_mask:0xf
	v_fmac_f32_dpp v234, v38, v198 row_shr:1 row_mask:0xf bank_mask:0xf
	v_fmac_f32_dpp v235, v39, v199 row_shr:1 row_mask:0xf bank_mask:0xf
	v_fmac_f32_dpp v232, v50, v158 row_shr:2 row_mask:0xf bank_mask:0xf
	v_fmac_f32_dpp v233, v51, v159 row_shr:2 row_mask:0xf bank_mask:0xf
	v_fmac_f32_dpp v234, v38, v190 row_shr:2 row_mask:0xf bank_mask:0xf
	v_fmac_f32_dpp v235, v39, v191 row_shr:2 row_mask:0xf bank_mask:0xf
	v_fmac_f32_dpp v232, v62, v166 row_shl:15 row_mask:0xf bank_mask:0xf
	v_fmac_f32_dpp v233, v63, v167 row_shl:15 row_mask:0xf bank_mask:0xf
	v_fmac_f32_dpp v234, v54, v198 row_shl:15 row_mask:0xf bank_mask:0xf
	v_fmac_f32_dpp v235, v55, v199 row_shl:15 row_mask:0xf bank_mask:0xf
	v_fmac_f32_dpp v232, v62, v158 row_shl:14 row_mask:0xf bank_mask:0xf
	v_fmac_f32_dpp v233, v63, v159 row_shl:14 row_mask:0xf bank_mask:0xf
	v_fmac_f32_dpp v234, v54, v190 row_shl:14 row_mask:0xf bank_mask:0xf
	v_fmac_f32_dpp v235, v55, v191 row_shl:14 row_mask:0xf bank_mask:0xf
	v_mul_f32_e32 v246, v236, v232
	v_mul_f32_e32 v247, v236, v233
	v_exp_f32_e32 v246, v246
	v_exp_f32_e32 v247, v247
	s_nop 0
	v_pk_add_f32 v[246:247], v[246:247], v[238:239]
	v_rcp_f32_e32 v246, v246
	v_rcp_f32_e32 v247, v247
	v_pk_mul_f32 v[232:233], v[232:233], v[234:235]
	v_pk_mul_f32 v[232:233], v[232:233], v[246:247]
	v_cvt_pk_bf16_f32 v49, v232, v233
	v_pk_fma_f32 v[232:233], v[62:63], v[174:175], v[182:183]
	v_pk_fma_f32 v[234:235], v[54:55], v[206:207], v[214:215]
	s_nop 1
	v_fmac_f32_dpp v232, v62, v166 row_shr:1 row_mask:0xf bank_mask:0xf
	v_fmac_f32_dpp v233, v63, v167 row_shr:1 row_mask:0xf bank_mask:0xf
	v_fmac_f32_dpp v234, v54, v198 row_shr:1 row_mask:0xf bank_mask:0xf
	v_fmac_f32_dpp v235, v55, v199 row_shr:1 row_mask:0xf bank_mask:0xf
	v_fmac_f32_dpp v232, v62, v158 row_shr:2 row_mask:0xf bank_mask:0xf
	v_fmac_f32_dpp v233, v63, v159 row_shr:2 row_mask:0xf bank_mask:0xf
	v_fmac_f32_dpp v234, v54, v190 row_shr:2 row_mask:0xf bank_mask:0xf
	v_fmac_f32_dpp v235, v55, v191 row_shr:2 row_mask:0xf bank_mask:0xf
	v_mul_f32_e32 v246, v236, v232
	v_mul_f32_e32 v247, v236, v233
	v_exp_f32_e32 v246, v246
; __device__ __forceinline__ unsigned cvt_pk_bf16(float lo, float hi) { unsigned r; asm("v_cvt_pk_bf16_f32 %0, %1, %2" : "=v"(r) : "v"(lo), "v"(hi)); return r; }
; __device__ __forceinline__ float sigmoid_f(float v) { return __builtin_amdgcn_rcpf(1.0f + __builtin_amdgcn_exp2f(-1.4426950409f * v)); }
; __device__ __forceinline__ f32x4 bf4(u32x2 w) { return (f32x4){bf_lo(w.x), bf_hi(w.x), bf_lo(w.y), bf_hi(w.y)}; }
; __device__ __forceinline__ void phase10(const Args& a, int G, int wv, bool dummy = false) {
;     ...
;             for (int t = 0; t < 8; ++t) { const f32x4 gc = bf4(gr[t]), vc = bf4(vr[t]);
;                 const f32x4 gg = wg0 * gm2 + wg1 * gm1 + wg2 * gc + bg, vv = wv0 * vm2 + wv1 * vm1 + wv2 * vc + bv;
;                 f32x4 o;
; #pragma unroll
;                 for (int e = 0; e < 4; ++e) o[e] = gg[e] * pg8::sigmoid_f(gg[e]) * vv[e];
;                 u32x2 w; w.x = cvt_pk_bf16(o[0], o[1]); w.y = cvt_pk_bf16(o[2], o[3]);
;                 if (dummy) *(u32x2*)((bf16_t*)(a.ws + WS_D) + ((((size_t)(row0 + t0 + t)) * 5632 + ch) & (size_t)0x1ffffff)) = w; else *(u32x2*)(up + (size_t)(t0 + t) * 5632) = w;
;                 gm2 = gm1; gm1 = gc; vm2 = vm1; vm1 = vc; }
	v_exp_f32_e32 v247, v247
	s_nop 0
	v_pk_add_f32 v[246:247], v[246:247], v[238:239]
	v_rcp_f32_e32 v246, v246
	v_rcp_f32_e32 v247, v247
	v_pk_mul_f32 v[232:233], v[232:233], v[234:235]
	v_pk_mul_f32 v[232:233], v[232:233], v[246:247]
	v_cvt_pk_bf16_f32 v61, v232, v233
	v_pk_fma_f32 v[232:233], v[8:9], v[176:177], v[184:185]
	v_pk_fma_f32 v[234:235], v[0:1], v[208:209], v[216:217]
	s_nop 1
	v_fmac_f32_dpp v232, v8, v168 row_shr:1 row_mask:0xf bank_mask:0xf
	v_fmac_f32_dpp v233, v9, v169 row_shr:1 row_mask:0xf bank_mask:0xf
	v_fmac_f32_dpp v234, v0, v200 row_shr:1 row_mask:0xf bank_mask:0xf
	v_fmac_f32_dpp v235, v1, v201 row_shr:1 row_mask:0xf bank_mask:0xf
	v_fmac_f32_dpp v232, v8, v160 row_shr:2 row_mask:0xf bank_mask:0xf
	v_fmac_f32_dpp v233, v9, v161 row_shr:2 row_mask:0xf bank_mask:0xf
	v_fmac_f32_dpp v234, v0, v192 row_shr:2 row_mask:0xf bank_mask:0xf
	v_fmac_f32_dpp v235, v1, v193 row_shr:2 row_mask:0xf bank_mask:0xf
	v_fmac_f32_dpp v232, v24, v168 row_shl:15 row_mask:0xf bank_mask:0xf
	v_fmac_f32_dpp v233, v25, v169 row_shl:15 row_mask:0xf bank_mask:0xf
	v_fmac_f32_dpp v234, v12, v200 row_shl:15 row_mask:0xf bank_mask:0xf
	v_fmac_f32_dpp v235, v13, v201 row_shl:15 row_mask:0xf bank_mask:0xf
	v_fmac_f32_dpp v232, v24, v160 row_shl:14 row_mask:0xf bank_mask:0xf
	v_fmac_f32_dpp v233, v25, v161 row_shl:14 row_mask:0xf bank_mask:0xf
	v_fmac_f32_dpp v234, v12, v192 row_shl:14 row_mask:0xf bank_mask:0xf
	v_fmac_f32_dpp v235, v13, v193 row_shl:14 row_mask:0xf bank_mask:0xf
	v_mul_f32_e32 v246, v236, v232
	v_mul_f32_e32 v247, v236, v233
	v_exp_f32_e32 v246, v246
	v_exp_f32_e32 v247, v247
	s_nop 0
	v_pk_add_f32 v[246:247], v[246:247], v[238:239]
	v_rcp_f32_e32 v246, v246
	v_rcp_f32_e32 v247, v247
	v_pk_mul_f32 v[232:233], v[232:233], v[234:235]
	v_pk_mul_f32 v[232:233], v[232:233], v[246:247]
	v_cvt_pk_bf16_f32 v18, v232, v233
	v_pk_fma_f32 v[232:233], v[24:25], v[176:177], v[184:185]
	v_pk_fma_f32 v[234:235], v[12:13], v[208:209], v[216:217]
	s_nop 1
	v_fmac_f32_dpp v232, v24, v168 row_shr:1 row_mask:0xf bank_mask:0xf
	v_fmac_f32_dpp v233, v25, v169 row_shr:1 row_mask:0xf bank_mask:0xf
	v_fmac_f32_dpp v234, v12, v200 row_shr:1 row_mask:0xf bank_mask:0xf
	v_fmac_f32_dpp v235, v13, v201 row_shr:1 row_mask:0xf bank_mask:0xf
	v_fmac_f32_dpp v232, v24, v160 row_shr:2 row_mask:0xf bank_mask:0xf
	v_fmac_f32_dpp v233, v25, v161 row_shr:2 row_mask:0xf bank_mask:0xf
	v_fmac_f32_dpp v234, v12, v192 row_shr:2 row_mask:0xf bank_mask:0xf
	v_fmac_f32_dpp v235, v13, v193 row_shr:2 row_mask:0xf bank_mask:0xf
	v_fmac_f32_dpp v232, v40, v168 row_shl:15 row_mask:0xf bank_mask:0xf
	v_fmac_f32_dpp v233, v41, v169 row_shl:15 row_mask:0xf bank_mask:0xf
	v_fmac_f32_dpp v234, v28, v200 row_shl:15 row_mask:0xf bank_mask:0xf
	v_fmac_f32_dpp v235, v29, v201 row_shl:15 row_mask:0xf bank_mask:0xf
	v_fmac_f32_dpp v232, v40, v160 row_shl:14 row_mask:0xf bank_mask:0xf
	v_fmac_f32_dpp v233, v41, v161 row_shl:14 row_mask:0xf bank_mask:0xf
	v_fmac_f32_dpp v234, v28, v192 row_shl:14 row_mask:0xf bank_mask:0xf
	v_fmac_f32_dpp v235, v29, v193 row_shl:14 row_mask:0xf bank_mask:0xf
	v_mul_f32_e32 v246, v236, v232
	v_mul_f32_e32 v247, v236, v233
	v_exp_f32_e32 v246, v246
	v_exp_f32_e32 v247, v247
	s_nop 0
	v_pk_add_f32 v[246:247], v[246:247], v[238:239]
	v_rcp_f32_e32 v246, v246
	v_rcp_f32_e32 v247, v247
	v_pk_mul_f32 v[232:233], v[232:233], v[234:235]
	v_pk_mul_f32 v[232:233], v[232:233], v[246:247]
	v_cvt_pk_bf16_f32 v34, v232, v233
	v_pk_fma_f32 v[232:233], v[40:41], v[176:177], v[184:185]
	v_pk_fma_f32 v[234:235], v[28:29], v[208:209], v[216:217]
	s_nop 1
	v_fmac_f32_dpp v232, v40, v168 row_shr:1 row_mask:0xf bank_mask:0xf
	v_fmac_f32_dpp v233, v41, v169 row_shr:1 row_mask:0xf bank_mask:0xf
	v_fmac_f32_dpp v234, v28, v200 row_shr:1 row_mask:0xf bank_mask:0xf
	v_fmac_f32_dpp v235, v29, v201 row_shr:1 row_mask:0xf bank_mask:0xf
	v_fmac_f32_dpp v232, v40, v160 row_shr:2 row_mask:0xf bank_mask:0xf
	v_fmac_f32_dpp v233, v41, v161 row_shr:2 row_mask:0xf bank_mask:0xf
	v_fmac_f32_dpp v234, v28, v192 row_shr:2 row_mask:0xf bank_mask:0xf
	v_fmac_f32_dpp v235, v29, v193 row_shr:2 row_mask:0xf bank_mask:0xf
	v_fmac_f32_dpp v232, v56, v168 row_shl:15 row_mask:0xf bank_mask:0xf
	v_fmac_f32_dpp v233, v57, v169 row_shl:15 row_mask:0xf bank_mask:0xf
	v_fmac_f32_dpp v234, v44, v200 row_shl:15 row_mask:0xf bank_mask:0xf
	v_fmac_f32_dpp v235, v45, v201 row_shl:15 row_mask:0xf bank_mask:0xf
	v_fmac_f32_dpp v232, v56, v160 row_shl:14 row_mask:0xf bank_mask:0xf
	v_fmac_f32_dpp v233, v57, v161 row_shl:14 row_mask:0xf bank_mask:0xf
	v_fmac_f32_dpp v234, v44, v192 row_shl:14 row_mask:0xf bank_mask:0xf
	v_fmac_f32_dpp v235, v45, v193 row_shl:14 row_mask:0xf bank_mask:0xf
	v_mul_f32_e32 v246, v236, v232
	v_mul_f32_e32 v247, v236, v233
	v_exp_f32_e32 v246, v246
	v_exp_f32_e32 v247, v247
	s_nop 0
	v_pk_add_f32 v[246:247], v[246:247], v[238:239]
	v_rcp_f32_e32 v246, v246
	v_rcp_f32_e32 v247, v247
	v_pk_mul_f32 v[232:233], v[232:233], v[234:235]
	v_pk_mul_f32 v[232:233], v[232:233], v[246:247]
	v_cvt_pk_bf16_f32 v50, v232, v233
	v_pk_fma_f32 v[232:233], v[56:57], v[176:177], v[184:185]
	v_pk_fma_f32 v[234:235], v[44:45], v[208:209], v[216:217]
	s_nop 1
	v_fmac_f32_dpp v232, v56, v168 row_shr:1 row_mask:0xf bank_mask:0xf
	v_fmac_f32_dpp v233, v57, v169 row_shr:1 row_mask:0xf bank_mask:0xf
	v_fmac_f32_dpp v234, v44, v200 row_shr:1 row_mask:0xf bank_mask:0xf
	v_fmac_f32_dpp v235, v45, v201 row_shr:1 row_mask:0xf bank_mask:0xf
	v_fmac_f32_dpp v232, v56, v160 row_shr:2 row_mask:0xf bank_mask:0xf
	v_fmac_f32_dpp v233, v57, v161 row_shr:2 row_mask:0xf bank_mask:0xf
	v_fmac_f32_dpp v234, v44, v192 row_shr:2 row_mask:0xf bank_mask:0xf
; __device__ __forceinline__ unsigned cvt_pk_bf16(float lo, float hi) { unsigned r; asm("v_cvt_pk_bf16_f32 %0, %1, %2" : "=v"(r) : "v"(lo), "v"(hi)); return r; }
; __device__ __forceinline__ float sigmoid_f(float v) { return __builtin_amdgcn_rcpf(1.0f + __builtin_amdgcn_exp2f(-1.4426950409f * v)); }
; __device__ __forceinline__ u32x4 pack8(f32x4 a, f32x4 b) { u32x4 w; w.x = cvt_pk_bf16(a[0], a[1]); w.y = cvt_pk_bf16(a[2], a[3]); w.z = cvt_pk_bf16(b[0], b[1]); w.w = cvt_pk_bf16(b[2], b[3]); return w; }
; __device__ __forceinline__ f32x4 bf4(u32x2 w) { return (f32x4){bf_lo(w.x), bf_hi(w.x), bf_lo(w.y), bf_hi(w.y)}; }
;     __device__ __forceinline__ void operator()(const f32x4 (&acc)[2][2][4][2], const Unit& u, int wr, int wc, int fr, int fq) const {
;     ...
;             for (int m = 0; m < 4; ++m) { const int row = row0 + ai * HALF + m * 16; bf16_t* rowp = UP + (size_t)row * 5632 + u.pn * HALF + wc * 32 + 8 * fq;
; #pragma unroll
;                 for (int bj = 0; bj < 2; ++bj) { const u32x4 w = pack8(acc[ai][bj][m][0], acc[ai][bj][m][1]); __builtin_nontemporal_store(w, (u32x4*)(rowp + (size_t)bj * ((size_t)16384 * 5632)));
; __device__ __forceinline__ void phase10(const Args& a, int G, int wv, bool dummy = false) {
;     ...
;             for (int t = 0; t < 8; ++t) { const f32x4 gc = bf4(gr[t]), vc = bf4(vr[t]);
;                 const f32x4 gg = wg0 * gm2 + wg1 * gm1 + wg2 * gc + bg, vv = wv0 * vm2 + wv1 * vm1 + wv2 * vc + bv;
;                 f32x4 o;
; #pragma unroll
;                 for (int e = 0; e < 4; ++e) o[e] = gg[e] * pg8::sigmoid_f(gg[e]) * vv[e];
;                 u32x2 w; w.x = cvt_pk_bf16(o[0], o[1]); w.y = cvt_pk_bf16(o[2], o[3]);
;                 if (dummy) *(u32x2*)((bf16_t*)(a.ws + WS_D) + ((((size_t)(row0 + t0 + t)) * 5632 + ch) & (size_t)0x1ffffff)) = w; else *(u32x2*)(up + (size_t)(t0 + t) * 5632) = w;
;                 gm2 = gm1; gm1 = gc; vm2 = vm1; vm1 = vc; }
	v_fmac_f32_dpp v235, v45, v193 row_shr:2 row_mask:0xf bank_mask:0xf
	v_mul_f32_e32 v246, v236, v232
	v_mul_f32_e32 v247, v236, v233
	v_exp_f32_e32 v246, v246
	v_exp_f32_e32 v247, v247
	s_nop 0
	v_pk_add_f32 v[246:247], v[246:247], v[238:239]
	v_rcp_f32_e32 v246, v246
	v_rcp_f32_e32 v247, v247
	v_pk_mul_f32 v[232:233], v[232:233], v[234:235]
	v_pk_mul_f32 v[232:233], v[232:233], v[246:247]
	v_cvt_pk_bf16_f32 v62, v232, v233
	v_pk_fma_f32 v[232:233], v[10:11], v[178:179], v[186:187]
	v_pk_fma_f32 v[234:235], v[2:3], v[210:211], v[218:219]
	s_nop 1
	v_fmac_f32_dpp v232, v10, v170 row_shr:1 row_mask:0xf bank_mask:0xf
	v_fmac_f32_dpp v233, v11, v171 row_shr:1 row_mask:0xf bank_mask:0xf
	v_fmac_f32_dpp v234, v2, v202 row_shr:1 row_mask:0xf bank_mask:0xf
	v_fmac_f32_dpp v235, v3, v203 row_shr:1 row_mask:0xf bank_mask:0xf
	v_fmac_f32_dpp v232, v10, v162 row_shr:2 row_mask:0xf bank_mask:0xf
	v_fmac_f32_dpp v233, v11, v163 row_shr:2 row_mask:0xf bank_mask:0xf
	v_fmac_f32_dpp v234, v2, v194 row_shr:2 row_mask:0xf bank_mask:0xf
	v_fmac_f32_dpp v235, v3, v195 row_shr:2 row_mask:0xf bank_mask:0xf
	v_fmac_f32_dpp v232, v26, v170 row_shl:15 row_mask:0xf bank_mask:0xf
	v_fmac_f32_dpp v233, v27, v171 row_shl:15 row_mask:0xf bank_mask:0xf
	v_fmac_f32_dpp v234, v14, v202 row_shl:15 row_mask:0xf bank_mask:0xf
	v_fmac_f32_dpp v235, v15, v203 row_shl:15 row_mask:0xf bank_mask:0xf
	v_fmac_f32_dpp v232, v26, v162 row_shl:14 row_mask:0xf bank_mask:0xf
	v_fmac_f32_dpp v233, v27, v163 row_shl:14 row_mask:0xf bank_mask:0xf
	v_fmac_f32_dpp v234, v14, v194 row_shl:14 row_mask:0xf bank_mask:0xf
	v_fmac_f32_dpp v235, v15, v195 row_shl:14 row_mask:0xf bank_mask:0xf
	v_mul_f32_e32 v246, v236, v232
	v_mul_f32_e32 v247, v236, v233
	v_exp_f32_e32 v246, v246
	v_exp_f32_e32 v247, v247
	s_nop 0
	v_pk_add_f32 v[246:247], v[246:247], v[238:239]
	v_rcp_f32_e32 v246, v246
	v_rcp_f32_e32 v247, v247
	v_pk_mul_f32 v[232:233], v[232:233], v[234:235]
	v_pk_mul_f32 v[232:233], v[232:233], v[246:247]
	v_cvt_pk_bf16_f32 v19, v232, v233
	v_pk_fma_f32 v[232:233], v[26:27], v[178:179], v[186:187]
	v_pk_fma_f32 v[234:235], v[14:15], v[210:211], v[218:219]
	s_nop 1
	v_fmac_f32_dpp v232, v26, v170 row_shr:1 row_mask:0xf bank_mask:0xf
	v_fmac_f32_dpp v233, v27, v171 row_shr:1 row_mask:0xf bank_mask:0xf
	v_fmac_f32_dpp v234, v14, v202 row_shr:1 row_mask:0xf bank_mask:0xf
	v_fmac_f32_dpp v235, v15, v203 row_shr:1 row_mask:0xf bank_mask:0xf
	v_fmac_f32_dpp v232, v26, v162 row_shr:2 row_mask:0xf bank_mask:0xf
	v_fmac_f32_dpp v233, v27, v163 row_shr:2 row_mask:0xf bank_mask:0xf
	v_fmac_f32_dpp v234, v14, v194 row_shr:2 row_mask:0xf bank_mask:0xf
	v_fmac_f32_dpp v235, v15, v195 row_shr:2 row_mask:0xf bank_mask:0xf
	v_fmac_f32_dpp v232, v42, v170 row_shl:15 row_mask:0xf bank_mask:0xf
	v_fmac_f32_dpp v233, v43, v171 row_shl:15 row_mask:0xf bank_mask:0xf
	v_fmac_f32_dpp v234, v30, v202 row_shl:15 row_mask:0xf bank_mask:0xf
	v_fmac_f32_dpp v235, v31, v203 row_shl:15 row_mask:0xf bank_mask:0xf
	v_fmac_f32_dpp v232, v42, v162 row_shl:14 row_mask:0xf bank_mask:0xf
	v_fmac_f32_dpp v233, v43, v163 row_shl:14 row_mask:0xf bank_mask:0xf
	v_fmac_f32_dpp v234, v30, v194 row_shl:14 row_mask:0xf bank_mask:0xf
	v_fmac_f32_dpp v235, v31, v195 row_shl:14 row_mask:0xf bank_mask:0xf
	v_mul_f32_e32 v246, v236, v232
	v_mul_f32_e32 v247, v236, v233
	v_exp_f32_e32 v246, v246
	v_exp_f32_e32 v247, v247
	s_nop 0
	v_pk_add_f32 v[246:247], v[246:247], v[238:239]
	v_rcp_f32_e32 v246, v246
	v_rcp_f32_e32 v247, v247
	v_pk_mul_f32 v[232:233], v[232:233], v[234:235]
	v_pk_mul_f32 v[232:233], v[232:233], v[246:247]
	v_cvt_pk_bf16_f32 v35, v232, v233
	v_pk_fma_f32 v[232:233], v[42:43], v[178:179], v[186:187]
	v_pk_fma_f32 v[234:235], v[30:31], v[210:211], v[218:219]
	s_nop 1
	v_fmac_f32_dpp v232, v42, v170 row_shr:1 row_mask:0xf bank_mask:0xf
	v_fmac_f32_dpp v233, v43, v171 row_shr:1 row_mask:0xf bank_mask:0xf
	v_fmac_f32_dpp v234, v30, v202 row_shr:1 row_mask:0xf bank_mask:0xf
	v_fmac_f32_dpp v235, v31, v203 row_shr:1 row_mask:0xf bank_mask:0xf
	v_fmac_f32_dpp v232, v42, v162 row_shr:2 row_mask:0xf bank_mask:0xf
	v_fmac_f32_dpp v233, v43, v163 row_shr:2 row_mask:0xf bank_mask:0xf
	v_fmac_f32_dpp v234, v30, v194 row_shr:2 row_mask:0xf bank_mask:0xf
	v_fmac_f32_dpp v235, v31, v195 row_shr:2 row_mask:0xf bank_mask:0xf
	v_fmac_f32_dpp v232, v58, v170 row_shl:15 row_mask:0xf bank_mask:0xf
	v_fmac_f32_dpp v233, v59, v171 row_shl:15 row_mask:0xf bank_mask:0xf
	v_fmac_f32_dpp v234, v46, v202 row_shl:15 row_mask:0xf bank_mask:0xf
	v_fmac_f32_dpp v235, v47, v203 row_shl:15 row_mask:0xf bank_mask:0xf
	v_fmac_f32_dpp v232, v58, v162 row_shl:14 row_mask:0xf bank_mask:0xf
	v_fmac_f32_dpp v233, v59, v163 row_shl:14 row_mask:0xf bank_mask:0xf
	v_fmac_f32_dpp v234, v46, v194 row_shl:14 row_mask:0xf bank_mask:0xf
	v_fmac_f32_dpp v235, v47, v195 row_shl:14 row_mask:0xf bank_mask:0xf
	v_mul_f32_e32 v246, v236, v232
	v_mul_f32_e32 v247, v236, v233
	v_exp_f32_e32 v246, v246
	v_exp_f32_e32 v247, v247
	s_nop 0
	v_pk_add_f32 v[246:247], v[246:247], v[238:239]
	v_rcp_f32_e32 v246, v246
	v_rcp_f32_e32 v247, v247
	v_pk_mul_f32 v[232:233], v[232:233], v[234:235]
	v_pk_mul_f32 v[232:233], v[232:233], v[246:247]
	v_cvt_pk_bf16_f32 v51, v232, v233
	v_pk_fma_f32 v[232:233], v[58:59], v[178:179], v[186:187]
	v_pk_fma_f32 v[234:235], v[46:47], v[210:211], v[218:219]
	s_nop 1
	v_fmac_f32_dpp v232, v58, v170 row_shr:1 row_mask:0xf bank_mask:0xf
	v_fmac_f32_dpp v233, v59, v171 row_shr:1 row_mask:0xf bank_mask:0xf
	v_fmac_f32_dpp v234, v46, v202 row_shr:1 row_mask:0xf bank_mask:0xf
	v_fmac_f32_dpp v235, v47, v203 row_shr:1 row_mask:0xf bank_mask:0xf
	v_fmac_f32_dpp v232, v58, v162 row_shr:2 row_mask:0xf bank_mask:0xf
	v_fmac_f32_dpp v233, v59, v163 row_shr:2 row_mask:0xf bank_mask:0xf
	v_fmac_f32_dpp v234, v46, v194 row_shr:2 row_mask:0xf bank_mask:0xf
	v_fmac_f32_dpp v235, v47, v195 row_shr:2 row_mask:0xf bank_mask:0xf
	v_mul_f32_e32 v246, v236, v232
	v_mul_f32_e32 v247, v236, v233
	v_exp_f32_e32 v246, v246
	v_exp_f32_e32 v247, v247
	s_nop 0
	v_pk_add_f32 v[246:247], v[246:247], v[238:239]
	v_rcp_f32_e32 v246, v246
	v_rcp_f32_e32 v247, v247
	v_pk_mul_f32 v[232:233], v[232:233], v[234:235]
	v_pk_mul_f32 v[232:233], v[232:233], v[246:247]
	v_cvt_pk_bf16_f32 v63, v232, v233
	s_add_u32 s36, s100, 0x160000
	s_addc_u32 s37, s101, 0
	s_andn2_b64 exec, exec, s[64:65]
	global_store_dwordx4 v149, v[60:63], s[36:37]
	s_mov_b64 exec, -1
	s_add_u32 s36, s100, 0x18c000
	s_addc_u32 s37, s101, 0
	global_store_dwordx4 v149, v[48:51], s[36:37]
	s_add_u32 s36, s100, 0x1b8000
	s_addc_u32 s37, s101, 0
	global_store_dwordx4 v149, v[32:35], s[36:37]
	s_add_u32 s36, s100, 0x1e4000
	s_addc_u32 s37, s101, 0
	global_store_dwordx4 v149, v[16:19], s[36:37]
	s_andn2_b64 vcc, exec, s[4:5]
	s_mov_b64 s[4:5], -1
	s_cbranch_vccnz .LBB0_961
	s_andn2_b64 vcc, exec, s[10:11]
	s_cbranch_vccnz .LBB0_960
	s_barrier
	s_branch .LBB0_960
